# v24 + QK waits trimmed to one counted lgkmcnt per K-fragment pair
# baseline (speedup 1.0000x reference)
; __device__ __forceinline__ void finishSM(f32x16& p0, f32x16& p1, float alpha, float& l_reg, bf16x8& pa0, bf16x8& pa1, bf16x8& pa2, bf16x8& pa3) {
; #pragma unroll
;   for (int r = 0; r < 16; ++r) p1[r] = __builtin_amdgcn_exp2f(p1[r]);
;   float ps = 0;
; #pragma unroll
;   for (int r = 0; r < 16; ++r) ps += p0[r];
; #pragma unroll
;   for (int r = 0; r < 16; ++r) ps += p1[r];
;   { auto rr = __builtin_amdgcn_permlane32_swap(__float_as_uint(ps), __float_as_uint(ps), false, false);
;     ps = __uint_as_float(rr[0]) + __uint_as_float(rr[1]); }
;   l_reg = l_reg * alpha + ps;
;   PK4(p0, 0, pa0); PK4(p0, 8, pa1); PK4(p1, 0, pa2); PK4(p1, 8, pa3);
; }
;   p0 = f32x16{}; p1 = f32x16{};
; #pragma unroll
;   for (int d0 = DLO; d0 < DHI; ++d0) { int cb = (d0 * 16 + hi * 8) * 2;
;     bf16x8 b0 = *reinterpret_cast<const bf16x8*>((const char*)Ks + KSWZ(r32, cb));
;     bf16x8 b1 = *reinterpret_cast<const bf16x8*>((const char*)Ks + KSWZ(32 + r32, cb));
;     p0 = __builtin_amdgcn_mfma_f32_32x32x16_bf16(b0, qr[d0], p0, 0, 0, 0);
;     p1 = __builtin_amdgcn_mfma_f32_32x32x16_bf16(b1, qr[d0], p1, 0, 0, 0); }
; }
; __device__ __forceinline__ int v_st(int k, int c) { const int kk = (k & ~0xC) | ((k & 4) << 1) | ((k & 8) >> 1); return ((kk >> 3) * 4 + (c >> 5)) * 512 + ((kk & 7) * 32 + (c & 31)) * 2; }
; __device__ __forceinline__ int v_rd_base(int lane) { return ((lane & 3) << 3) | (((lane >> 2) & 3) << 6) | (((lane >> 4) & 1) << 5) | (((lane >> 5) & 1) << 8); }
; template <int OFF> __device__ __forceinline__ s16x4 tr_read(int vb) {
;   s16x4 r; asm volatile("ds_read_b64_tr_b16 %0, %1 offset:%2" : "=&v"(r) : "v"(vb), "i"(OFF) : "memory"); return r;
; }
; template <int D0> __device__ __forceinline__ void pv_one(f32x16& od, int vb, bf16x8 pa0, bf16x8 pa1, bf16x8 pa2, bf16x8 pa3) {
; template <int DLO, int DHI>
; __device__ __forceinline__ void attn_dense_body(const int g_wave, const bf16* __restrict__ Qb, const bf16* __restrict__ Kh, const bf16* __restrict__ Vh,
;                                                 bf16* __restrict__ Ob, int ldo, char* lds) {
;     ...
;     SBAR(); qkt<DLO, DHI>(pB0, pB1, (bf16*)((char*)K_lds + SHM_K), qr, r32, hi);
;     finishSM(pA0, pA1, alA, l_reg, pa0, pa1, pa2, pa3); SBAR();
;     SLOAD(SO, (j + 2) * KVBLK); SBAR();
;     pv_d0(o, vb0, pa0, pa1, pa2, pa3); partialSM(pB0, pB1, m_reg, mnB, alB);
;     __syncthreads(); SWAIT(); SWRITE(0, SE);
.LBB0_1002:
	ds_read_b128 v[66:69], v190 offset:49152
	ds_read_b128 v[70:73], v190 offset:57344
	ds_read_b128 v[186:189], v194 offset:49152
	ds_read_b128 v[208:211], v194 offset:57344
	ds_read_b128 v[232:235], v195 offset:49152
	ds_read_b128 v[236:239], v195 offset:57344
	ds_read_b128 v[240:243], v196 offset:49152
	ds_read_b128 v[244:247], v196 offset:57344
	v_add_f32_e32 v146, 0, v161
	v_add_f32_e32 v146, v167, v146
	v_add_f32_e32 v146, v147, v146
	s_waitcnt lgkmcnt(6)
	v_mfma_f32_32x32x16_bf16 v[82:97], v[66:69], v[102:105], 0
	v_add_f32_e32 v146, v166, v146
	v_add_f32_e32 v146, v148, v146
	v_add_f32_e32 v146, v160, v146
	v_add_f32_e32 v146, v149, v146
	v_add_f32_e32 v146, v159, v146
	v_add_f32_e32 v146, v156, v146
	v_mfma_f32_32x32x16_bf16 v[66:81], v[70:73], v[102:105], 0
	v_add_f32_e32 v146, v158, v146
	v_add_f32_e32 v146, v154, v146
	v_add_f32_e32 v146, v157, v146
	v_exp_f32_e32 v142, v142
	v_add_f32_e32 v146, v152, v146
	v_exp_f32_e32 v143, v143
	v_add_f32_e32 v146, v155, v146
	s_waitcnt lgkmcnt(4)
	v_mfma_f32_32x32x16_bf16 v[82:97], v[186:189], v[98:101], v[82:97]
	v_exp_f32_e32 v140, v140
	v_add_f32_e32 v146, v151, v146
	v_exp_f32_e32 v141, v141
	v_add_f32_e32 v146, v153, v146
	v_exp_f32_e32 v134, v134
	v_add_f32_e32 v146, v142, v146
	v_exp_f32_e32 v135, v135
	v_mfma_f32_32x32x16_bf16 v[66:81], v[208:211], v[98:101], v[66:81]
	v_add_f32_e32 v146, v143, v146
	v_exp_f32_e32 v132, v132
	v_add_f32_e32 v146, v140, v146
	v_exp_f32_e32 v133, v133
	v_add_f32_e32 v146, v141, v146
	v_exp_f32_e32 v130, v130
	s_waitcnt lgkmcnt(2)
	v_mfma_f32_32x32x16_bf16 v[82:97], v[232:235], v[106:109], v[82:97]
	v_add_f32_e32 v146, v134, v146
	v_exp_f32_e32 v131, v131
	v_add_f32_e32 v146, v135, v146
	v_exp_f32_e32 v144, v144
	v_add_f32_e32 v146, v132, v146
	v_exp_f32_e32 v145, v145
	v_add_f32_e32 v146, v133, v146
	v_mfma_f32_32x32x16_bf16 v[66:81], v[236:239], v[106:109], v[66:81]
	v_exp_f32_e32 v138, v138
	v_add_f32_e32 v146, v130, v146
	v_exp_f32_e32 v139, v139
	v_add_f32_e32 v146, v131, v146
	v_exp_f32_e32 v136, v136
	v_add_f32_e32 v146, v144, v146
	s_waitcnt lgkmcnt(0)
	v_mfma_f32_32x32x16_bf16 v[82:97], v[240:243], v[110:113], v[82:97]
	v_exp_f32_e32 v137, v137
	v_add_f32_e32 v146, v145, v146
	v_add_f32_e32 v146, v138, v146
	v_add_f32_e32 v146, v139, v146
	v_add_f32_e32 v146, v136, v146
	v_add_f32_e32 v207, v137, v146
	v_cvt_pk_bf16_f32 v146, v161, v167
	v_mfma_f32_32x32x16_bf16 v[66:81], v[244:247], v[110:113], v[66:81]
	v_mov_b32_e32 v208, v207
	v_cvt_pk_bf16_f32 v147, v147, v166
	v_cvt_pk_bf16_f32 v148, v148, v160
	s_nop 1
	v_permlane32_swap_b32_e32 v207, v208
	v_cvt_pk_bf16_f32 v149, v149, v159
	v_permlane32_swap_b32_e32 v146, v148
	v_cvt_pk_bf16_f32 v156, v156, v158
	v_cvt_pk_bf16_f32 v157, v154, v157
	v_cvt_pk_bf16_f32 v158, v152, v155
	v_cvt_pk_bf16_f32 v159, v151, v153
	v_cvt_pk_bf16_f32 v152, v142, v143
	v_cvt_pk_bf16_f32 v153, v140, v141
	v_cvt_pk_bf16_f32 v154, v134, v135
	v_cvt_pk_bf16_f32 v155, v132, v133
	v_cvt_pk_bf16_f32 v186, v130, v131
	v_cvt_pk_bf16_f32 v187, v144, v145
	v_cvt_pk_bf16_f32 v188, v138, v139
	v_cvt_pk_bf16_f32 v189, v136, v137
	v_permlane32_swap_b32_e32 v147, v149
	v_permlane32_swap_b32_e32 v156, v158
	v_permlane32_swap_b32_e32 v157, v159
	v_permlane32_swap_b32_e32 v152, v154
	v_permlane32_swap_b32_e32 v153, v155
	v_permlane32_swap_b32_e32 v186, v188
	v_permlane32_swap_b32_e32 v187, v189
	s_waitcnt vmcnt(0)
	ds_write_b128 v192, v[114:117]
	ds_write_b128 v193, v[118:121]
	ds_write_b128 v177, v[122:125] offset:32768
	ds_write_b128 v191, v[126:129] offset:32768
	v_lshl_add_u64 v[168:169], v[164:165], 0, v[0:1]
	s_mov_b32 s1, 0x18fb0000
	v_add_co_u32_e32 v130, vcc, s1, v168
	s_mov_b32 s1, 0x18ff8000
	s_nop 0
	v_addc_co_u32_e32 v131, vcc, 0, v169, vcc
	v_add_co_u32_e32 v134, vcc, s1, v168
	v_lshl_add_u64 v[166:167], v[162:163], 0, v[0:1]
	s_nop 0
	v_addc_co_u32_e32 v135, vcc, 0, v169, vcc
	s_mov_b32 s1, 0x1f648000
	v_add_co_u32_e32 v138, vcc, s1, v166
	s_mov_b32 s1, 0x1f654000
	s_nop 0
	v_addc_co_u32_e32 v139, vcc, 0, v167, vcc
	v_add_co_u32_e32 v142, vcc, s1, v166
	global_load_dwordx4 v[130:133], v[130:131], off
	s_nop 0
	global_load_dwordx4 v[134:137], v[134:135], off
	v_addc_co_u32_e32 v143, vcc, 0, v167, vcc
	global_load_dwordx4 v[138:141], v[138:139], off
	s_nop 0
	global_load_dwordx4 v[142:145], v[142:143], off
	ds_read_b64_tr_b16 v[210:211], v176 offset:0
	ds_read_b64_tr_b16 v[212:213], v176 offset:0x800
	ds_read_b64_tr_b16 v[214:215], v176 offset:0x1000
	ds_read_b64_tr_b16 v[216:217], v176 offset:0x1800
	ds_read_b64_tr_b16 v[218:219], v176 offset:0x2000
	ds_read_b64_tr_b16 v[220:221], v176 offset:0x2800
	ds_read_b64_tr_b16 v[222:223], v176 offset:0x3000
	ds_read_b64_tr_b16 v[224:225], v176 offset:0x3800
	s_waitcnt lgkmcnt(4)
	s_nop 0
	v_mfma_f32_32x32x16_bf16 v[2:17], v[146:149], v[210:213], v[2:17]
	ds_read_b64_tr_b16 v[210:211], v176 offset:0x200
	ds_read_b64_tr_b16 v[212:213], v176 offset:0xa00
	v_mfma_f32_32x32x16_bf16 v[2:17], v[156:159], v[214:217], v[2:17]
	ds_read_b64_tr_b16 v[214:215], v176 offset:0x1200
	ds_read_b64_tr_b16 v[216:217], v176 offset:0x1a00
	s_waitcnt lgkmcnt(4)
	v_mfma_f32_32x32x16_bf16 v[2:17], v[152:155], v[218:221], v[2:17]
	ds_read_b64_tr_b16 v[218:219], v176 offset:0x2200
	ds_read_b64_tr_b16 v[220:221], v176 offset:0x2a00
	v_mfma_f32_32x32x16_bf16 v[2:17], v[186:189], v[222:225], v[2:17]
	ds_read_b64_tr_b16 v[222:223], v176 offset:0x3200
	ds_read_b64_tr_b16 v[224:225], v176 offset:0x3a00
	s_waitcnt lgkmcnt(4)
; #define SBAR() __builtin_amdgcn_sched_barrier(0)
; __device__ __forceinline__ void partialSM(f32x16& p0, f32x16& p1, float& m_reg, float& mn, float& alpha) {
;   constexpr float C = SCALE * 1.4426950408889634f;
;   float pmax = p0[0];
; #pragma unroll
;   for (int r = 1; r < 16; ++r) pmax = fmaxf(pmax, p0[r]);
; #pragma unroll
;   for (int r = 0; r < 16; ++r) pmax = fmaxf(pmax, p1[r]);
;   { auto rr = __builtin_amdgcn_permlane32_swap(__float_as_uint(pmax), __float_as_uint(pmax), false, false);
;     pmax = fmaxf(__uint_as_float(rr[0]), __uint_as_float(rr[1])); }
;   if (__builtin_expect(__all(pmax - m_reg <= THR / SCALE), 1)) { mn = m_reg; alpha = 1.f; }
;   else { mn = fmaxf(m_reg, pmax); alpha = __builtin_amdgcn_exp2f((m_reg - mn) * C); m_reg = mn; }
; template <int D0> __device__ __forceinline__ void pv_one(f32x16& od, int vb, bf16x8 pa0, bf16x8 pa1, bf16x8 pa2, bf16x8 pa3) {
;   const s16x4 l0 = tr_read<v_rd_off(D0, 0, 0)>(vb), h0 = tr_read<v_rd_off(D0, 0, 1)>(vb), l1 = tr_read<v_rd_off(D0, 1, 0)>(vb), h1 = tr_read<v_rd_off(D0, 1, 1)>(vb);
;   const s16x4 l2 = tr_read<v_rd_off(D0, 2, 0)>(vb), h2 = tr_read<v_rd_off(D0, 2, 1)>(vb), l3 = tr_read<v_rd_off(D0, 3, 0)>(vb), h3 = tr_read<v_rd_off(D0, 3, 1)>(vb);
;   asm volatile("s_waitcnt lgkmcnt(0)" ::: "memory"); SBAR();
;     ...
;   od = __builtin_amdgcn_mfma_f32_32x32x16_bf16(pa0, PK(l0, h0), od, 0, 0, 0);
;   od = __builtin_amdgcn_mfma_f32_32x32x16_bf16(pa1, PK(l1, h1), od, 0, 0, 0);
;   od = __builtin_amdgcn_mfma_f32_32x32x16_bf16(pa2, PK(l2, h2), od, 0, 0, 0);
;   od = __builtin_amdgcn_mfma_f32_32x32x16_bf16(pa3, PK(l3, h3), od, 0, 0, 0);
;     ...
; }
; __device__ __forceinline__ void pv_d0(f32x16* o, int vb, bf16x8 pa0, bf16x8 pa1, bf16x8 pa2, bf16x8 pa3) {
;   pv_one<0>(o[0], vb, pa0, pa1, pa2, pa3); pv_one<1>(o[1], vb, pa0, pa1, pa2, pa3); pv_one<2>(o[2], vb, pa0, pa1, pa2, pa3); pv_one<3>(o[3], vb, pa0, pa1, pa2, pa3);
	v_mfma_f32_32x32x16_bf16 v[50:65], v[146:149], v[210:213], v[50:65]
	ds_read_b64_tr_b16 v[210:211], v176 offset:0x400
	ds_read_b64_tr_b16 v[212:213], v176 offset:0xc00
	v_mfma_f32_32x32x16_bf16 v[50:65], v[156:159], v[214:217], v[50:65]
	ds_read_b64_tr_b16 v[214:215], v176 offset:0x1400
	ds_read_b64_tr_b16 v[216:217], v176 offset:0x1c00
	s_waitcnt lgkmcnt(4)
	v_mfma_f32_32x32x16_bf16 v[50:65], v[152:155], v[218:221], v[50:65]
	ds_read_b64_tr_b16 v[218:219], v176 offset:0x2400
	ds_read_b64_tr_b16 v[220:221], v176 offset:0x2c00
	v_mfma_f32_32x32x16_bf16 v[50:65], v[186:189], v[222:225], v[50:65]
	ds_read_b64_tr_b16 v[222:223], v176 offset:0x3400
	ds_read_b64_tr_b16 v[224:225], v176 offset:0x3c00
	s_waitcnt lgkmcnt(4)
	v_mfma_f32_32x32x16_bf16 v[34:49], v[146:149], v[210:213], v[34:49]
	ds_read_b64_tr_b16 v[210:211], v176 offset:0x600
	ds_read_b64_tr_b16 v[212:213], v176 offset:0xe00
	v_mfma_f32_32x32x16_bf16 v[34:49], v[156:159], v[214:217], v[34:49]
	ds_read_b64_tr_b16 v[214:215], v176 offset:0x1600
	ds_read_b64_tr_b16 v[216:217], v176 offset:0x1e00
	s_waitcnt lgkmcnt(4)
	v_mfma_f32_32x32x16_bf16 v[34:49], v[152:155], v[218:221], v[34:49]
	ds_read_b64_tr_b16 v[218:219], v176 offset:0x2600
	ds_read_b64_tr_b16 v[220:221], v176 offset:0x2e00
	v_mfma_f32_32x32x16_bf16 v[34:49], v[186:189], v[222:225], v[34:49]
	ds_read_b64_tr_b16 v[222:223], v176 offset:0x3600
	ds_read_b64_tr_b16 v[224:225], v176 offset:0x3e00
	s_waitcnt lgkmcnt(4)
	v_mfma_f32_32x32x16_bf16 v[18:33], v[146:149], v[210:213], v[18:33]
	v_max_f32_e32 v146, v83, v83
	v_max_f32_e32 v147, v82, v82
	v_max_f32_e32 v146, v147, v146
	v_max3_f32 v146, v146, v84, v85
	v_max3_f32 v146, v146, v86, v87
	v_max3_f32 v146, v146, v88, v89
	v_max3_f32 v146, v146, v90, v91
	v_max3_f32 v146, v146, v92, v93
	v_max3_f32 v146, v146, v94, v95
	v_mfma_f32_32x32x16_bf16 v[18:33], v[156:159], v[214:217], v[18:33]
	v_max3_f32 v146, v146, v96, v97
	v_max3_f32 v146, v146, v66, v67
	v_max3_f32 v146, v146, v68, v69
	v_max3_f32 v146, v146, v70, v71
	v_max3_f32 v146, v146, v72, v73
	v_max3_f32 v146, v146, v74, v75
	v_max3_f32 v146, v146, v76, v77
	v_max3_f32 v146, v146, v78, v79
	s_waitcnt lgkmcnt(0)
	v_mfma_f32_32x32x16_bf16 v[18:33], v[152:155], v[218:221], v[18:33]
	v_max3_f32 v146, v146, v80, v81
	v_mov_b32_e32 v147, v146
	s_nop 1
	v_permlane32_swap_b32_e32 v146, v147
	v_max_f32_e32 v147, v147, v147
	v_max_f32_e32 v146, v146, v146
	v_max_f32_e32 v146, v146, v147
	v_sub_f32_e32 v147, v146, v150
	v_cmp_ge_f32_e32 vcc, s63, v147
	v_max_f32_e32 v147, v150, v150
	v_max_f32_e32 v146, v147, v146
	v_mfma_f32_32x32x16_bf16 v[18:33], v[186:189], v[222:225], v[18:33]
	v_sub_f32_e32 v147, v150, v146
	v_mul_f32_e32 v147, 0x3e0293ee, v147
	v_exp_f32_e32 v147, v147
	s_cmp_eq_u64 vcc, exec
	s_cselect_b64 s[8:9], -1, 0
	s_waitcnt vmcnt(4)
	v_cndmask_b32_e64 v209, v147, 1.0, s[8:9]
	v_cmp_gt_f32_e32 vcc, 1.0, v209
	s_cbranch_vccz .LBB0_1006
	s_and_saveexec_b64 s[2:3], s[6:7]
	ds_write_b32 v173, v209 offset:128
	s_or_b64 exec, exec, s[2:3]
	s_waitcnt lgkmcnt(0)
	v_add_u32_e32 v147, s15, v172
	ds_read_b128 v[152:155], v147 offset:224
	ds_read_b128 v[156:159], v147 offset:192
	ds_read_b128 v[186:189], v147 offset:160
	ds_read_b128 v[210:213], v147 offset:128
	s_waitcnt lgkmcnt(3)
	v_pk_mul_f32 v[14:15], v[14:15], v[152:153]
	s_waitcnt lgkmcnt(2)
	v_pk_mul_f32 v[10:11], v[10:11], v[156:157]
	s_waitcnt lgkmcnt(1)
	v_pk_mul_f32 v[6:7], v[6:7], v[186:187]
	v_pk_mul_f32 v[16:17], v[16:17], v[154:155]
	v_pk_mul_f32 v[12:13], v[12:13], v[158:159]
	v_pk_mul_f32 v[8:9], v[8:9], v[188:189]
	s_waitcnt lgkmcnt(0)
	v_pk_mul_f32 v[4:5], v[4:5], v[212:213]
	v_pk_mul_f32 v[2:3], v[2:3], v[210:211]
	v_pk_mul_f32 v[62:63], v[62:63], v[152:153]
	v_pk_mul_f32 v[58:59], v[58:59], v[156:157]
	v_pk_mul_f32 v[54:55], v[54:55], v[186:187]
	v_pk_mul_f32 v[64:65], v[64:65], v[154:155]
	v_pk_mul_f32 v[60:61], v[60:61], v[158:159]
	v_pk_mul_f32 v[56:57], v[56:57], v[188:189]
	v_pk_mul_f32 v[52:53], v[52:53], v[212:213]
	v_pk_mul_f32 v[50:51], v[50:51], v[210:211]
	v_pk_mul_f32 v[46:47], v[46:47], v[152:153]
	v_pk_mul_f32 v[42:43], v[42:43], v[156:157]
	v_pk_mul_f32 v[38:39], v[38:39], v[186:187]
	v_pk_mul_f32 v[48:49], v[48:49], v[154:155]
	v_pk_mul_f32 v[44:45], v[44:45], v[158:159]
	v_pk_mul_f32 v[40:41], v[40:41], v[188:189]
	v_pk_mul_f32 v[36:37], v[36:37], v[212:213]
	v_pk_mul_f32 v[34:35], v[34:35], v[210:211]
	v_pk_mul_f32 v[30:31], v[30:31], v[152:153]
	v_pk_mul_f32 v[26:27], v[26:27], v[156:157]
	v_pk_mul_f32 v[22:23], v[22:23], v[186:187]
	v_pk_mul_f32 v[32:33], v[32:33], v[154:155]
	v_pk_mul_f32 v[28:29], v[28:29], v[158:159]
	v_pk_mul_f32 v[24:25], v[24:25], v[188:189]
	v_pk_mul_f32 v[20:21], v[20:21], v[212:213]
	v_pk_mul_f32 v[18:19], v[18:19], v[210:211]
; #define SBAR() __builtin_amdgcn_sched_barrier(0)
; __device__ __forceinline__ void partialSM(f32x16& p0, f32x16& p1, float& m_reg, float& mn, float& alpha) {
;     ...
;   float mnC = -mn * C;
; #pragma unroll
;   for (int r = 0; r < 16; ++r) p0[r] = fmaf(p0[r], C, mnC);
; #pragma unroll
;   for (int r = 0; r < 16; ++r) p1[r] = fmaf(p1[r], C, mnC);
; #pragma unroll
;   for (int r = 0; r < 16; ++r) p0[r] = __builtin_amdgcn_exp2f(p0[r]);
; }
; __device__ __forceinline__ void finishSM(f32x16& p0, f32x16& p1, float alpha, float& l_reg, bf16x8& pa0, bf16x8& pa1, bf16x8& pa2, bf16x8& pa3) {
; #pragma unroll
;   for (int r = 0; r < 16; ++r) p1[r] = __builtin_amdgcn_exp2f(p1[r]);
;   float ps = 0;
; #pragma unroll
;   for (int r = 0; r < 16; ++r) ps += p0[r];
; #pragma unroll
;   for (int r = 0; r < 16; ++r) ps += p1[r];
;   { auto rr = __builtin_amdgcn_permlane32_swap(__float_as_uint(ps), __float_as_uint(ps), false, false);
;     ps = __uint_as_float(rr[0]) + __uint_as_float(rr[1]); }
;   l_reg = l_reg * alpha + ps;
;   PK4(p0, 0, pa0); PK4(p0, 8, pa1); PK4(p1, 0, pa2); PK4(p1, 8, pa3);
; }
;   p0 = f32x16{}; p1 = f32x16{};
; #pragma unroll
;   for (int d0 = DLO; d0 < DHI; ++d0) { int cb = (d0 * 16 + hi * 8) * 2;
;     bf16x8 b0 = *reinterpret_cast<const bf16x8*>((const char*)Ks + KSWZ(r32, cb));
;     bf16x8 b1 = *reinterpret_cast<const bf16x8*>((const char*)Ks + KSWZ(32 + r32, cb));
; template <int DLO, int DHI>
; __device__ __forceinline__ void attn_dense_body(const int g_wave, const bf16* __restrict__ Qb, const bf16* __restrict__ Kh, const bf16* __restrict__ Vh,
;                                                 bf16* __restrict__ Ob, int ldo, char* lds) {
;     ...
;     SBAR(); qkt<DLO, DHI>(pB0, pB1, (bf16*)((char*)K_lds + SHM_K), qr, r32, hi);
;     finishSM(pA0, pA1, alA, l_reg, pa0, pa1, pa2, pa3); SBAR();
;     SLOAD(SO, (j + 2) * KVBLK); SBAR();
;     pv_d0(o, vb0, pa0, pa1, pa2, pa3); partialSM(pB0, pB1, m_reg, mnB, alB);
;     __syncthreads(); SWAIT(); SWRITE(0, SE);
;     RESC(alB); __syncthreads();
;     SBAR(); qkt<DLO, DHI>(pA0, pA1, K_lds, qr, r32, hi);
;     finishSM(pB0, pB1, alB, l_reg, pa0, pa1, pa2, pa3); SBAR();
;     if (j + 3 < NT) SLOAD(SE, (j + 3) * KVBLK); SBAR();
;     pv_d0(o, vb0 + (int)SHM_V, pa0, pa1, pa2, pa3); partialSM(pA0, pA1, m_reg, mnA, alA);
;     __syncthreads(); SWAIT(); SWRITE(1, SO);
;     RESC(alA); __syncthreads();
.LBB0_1006:
	v_cndmask_b32_e64 v210, v146, v150, s[8:9]
	v_mul_f32_e32 v211, 0xbe0293ee, v210
	v_fmamk_f32 v82, v82, 0x3e0293ee, v211
	v_fmamk_f32 v83, v83, 0x3e0293ee, v211
	v_fmamk_f32 v84, v84, 0x3e0293ee, v211
	v_fmamk_f32 v85, v85, 0x3e0293ee, v211
	v_fmamk_f32 v86, v86, 0x3e0293ee, v211
	v_fmamk_f32 v87, v87, 0x3e0293ee, v211
	v_fmamk_f32 v88, v88, 0x3e0293ee, v211
	v_fmamk_f32 v89, v89, 0x3e0293ee, v211
	v_fmamk_f32 v90, v90, 0x3e0293ee, v211
	v_fmamk_f32 v91, v91, 0x3e0293ee, v211
	v_fmamk_f32 v92, v92, 0x3e0293ee, v211
	v_fmamk_f32 v93, v93, 0x3e0293ee, v211
	v_fmamk_f32 v94, v94, 0x3e0293ee, v211
	v_fmamk_f32 v95, v95, 0x3e0293ee, v211
	v_fmamk_f32 v96, v96, 0x3e0293ee, v211
	v_fmamk_f32 v97, v97, 0x3e0293ee, v211
	v_exp_f32_e32 v146, v82
	v_exp_f32_e32 v161, v83
	v_exp_f32_e32 v147, v84
	v_exp_f32_e32 v160, v85
	v_exp_f32_e32 v148, v86
	v_exp_f32_e32 v159, v87
	v_exp_f32_e32 v149, v88
	v_exp_f32_e32 v158, v89
	v_exp_f32_e32 v150, v90
	v_exp_f32_e32 v157, v91
	v_exp_f32_e32 v151, v92
	v_exp_f32_e32 v156, v93
	v_exp_f32_e32 v152, v94
	v_exp_f32_e32 v155, v95
	v_exp_f32_e32 v153, v96
	v_exp_f32_e32 v154, v97
	v_fmamk_f32 v220, v66, 0x3e0293ee, v211
	v_fmamk_f32 v221, v67, 0x3e0293ee, v211
	v_fmamk_f32 v222, v68, 0x3e0293ee, v211
	v_fmamk_f32 v223, v69, 0x3e0293ee, v211
	v_fmamk_f32 v224, v70, 0x3e0293ee, v211
	v_fmamk_f32 v213, v71, 0x3e0293ee, v211
	v_fmamk_f32 v214, v72, 0x3e0293ee, v211
	v_fmamk_f32 v215, v73, 0x3e0293ee, v211
	v_fmamk_f32 v216, v74, 0x3e0293ee, v211
	v_fmamk_f32 v217, v75, 0x3e0293ee, v211
	v_fmamk_f32 v218, v76, 0x3e0293ee, v211
	v_fmamk_f32 v219, v77, 0x3e0293ee, v211
	v_fmamk_f32 v212, v78, 0x3e0293ee, v211
	v_fmamk_f32 v225, v79, 0x3e0293ee, v211
	v_fmamk_f32 v226, v80, 0x3e0293ee, v211
	v_fmac_f32_e32 v211, 0x3e0293ee, v81
	v_xor_b32_e32 v190, 0x10000, v190
	v_xor_b32_e32 v194, 0x10000, v194
	v_xor_b32_e32 v195, 0x10000, v195
	v_xor_b32_e32 v196, 0x10000, v196
	s_waitcnt lgkmcnt(0)
	s_barrier
	ds_read_b128 v[66:69], v190 offset:32768
	ds_read_b128 v[70:73], v190 offset:40960
	ds_read_b128 v[232:235], v194 offset:32768
	ds_read_b128 v[236:239], v194 offset:40960
	ds_read_b128 v[240:243], v195 offset:32768
	ds_read_b128 v[244:247], v195 offset:40960
	ds_read_b128 v[248:251], v196 offset:32768
	ds_read_b128 v[114:117], v196 offset:40960
	v_exp_f32_e32 v213, v213
	v_exp_f32_e32 v214, v214
	s_waitcnt lgkmcnt(6)
	v_mfma_f32_32x32x16_bf16 v[82:97], v[66:69], v[102:105], 0
	v_exp_f32_e32 v215, v215
	v_exp_f32_e32 v216, v216
	v_exp_f32_e32 v217, v217
	v_exp_f32_e32 v218, v218
	v_exp_f32_e32 v219, v219
	v_mfma_f32_32x32x16_bf16 v[66:81], v[70:73], v[102:105], 0
	s_waitcnt lgkmcnt(4)
	v_mfma_f32_32x32x16_bf16 v[82:97], v[232:235], v[98:101], v[82:97]
	v_mfma_f32_32x32x16_bf16 v[66:81], v[236:239], v[98:101], v[66:81]
	s_waitcnt lgkmcnt(2)
	v_mfma_f32_32x32x16_bf16 v[82:97], v[240:243], v[106:109], v[82:97]
	v_mfma_f32_32x32x16_bf16 v[66:81], v[244:247], v[106:109], v[66:81]
	s_waitcnt lgkmcnt(0)
	v_mfma_f32_32x32x16_bf16 v[82:97], v[248:251], v[110:113], v[82:97]
	v_exp_f32_e32 v186, v220
	v_exp_f32_e32 v220, v224
	v_exp_f32_e32 v224, v211
	v_add_f32_e32 v211, 0, v146
	v_add_f32_e32 v211, v161, v211
	v_add_f32_e32 v211, v147, v211
	v_add_f32_e32 v211, v160, v211
	v_add_f32_e32 v211, v148, v211
	v_add_f32_e32 v211, v159, v211
	v_add_f32_e32 v211, v149, v211
	v_add_f32_e32 v211, v158, v211
	v_add_f32_e32 v211, v150, v211
	v_add_f32_e32 v211, v157, v211
	v_add_f32_e32 v211, v151, v211
	v_add_f32_e32 v211, v156, v211
	v_add_f32_e32 v211, v152, v211
	v_exp_f32_e32 v187, v221
	v_add_f32_e32 v211, v155, v211
	v_exp_f32_e32 v188, v222
	v_add_f32_e32 v211, v153, v211
	v_exp_f32_e32 v189, v223
	v_add_f32_e32 v211, v154, v211
	v_add_f32_e32 v211, v186, v211
	v_add_f32_e32 v211, v187, v211
	v_add_f32_e32 v211, v188, v211
	v_add_f32_e32 v211, v189, v211
	v_add_f32_e32 v211, v220, v211
	v_add_f32_e32 v211, v213, v211
	v_add_f32_e32 v211, v214, v211
	v_add_f32_e32 v211, v215, v211
	v_exp_f32_e32 v221, v212
	v_add_f32_e32 v211, v216, v211
	v_exp_f32_e32 v222, v225
	v_add_f32_e32 v211, v217, v211
	v_mfma_f32_32x32x16_bf16 v[66:81], v[114:117], v[110:113], v[66:81]
	v_exp_f32_e32 v223, v226
	v_add_f32_e32 v211, v218, v211
	v_add_f32_e32 v211, v219, v211
	v_add_f32_e32 v211, v221, v211
	v_add_f32_e32 v211, v222, v211
	v_add_f32_e32 v211, v223, v211
	v_add_f32_e32 v211, v224, v211
	v_mov_b32_e32 v212, v211
	v_cvt_pk_bf16_f32 v146, v146, v161
	v_cvt_pk_bf16_f32 v147, v147, v160
	v_cvt_pk_bf16_f32 v148, v148, v159
	v_cvt_pk_bf16_f32 v149, v149, v158
	v_cvt_pk_bf16_f32 v150, v150, v157
	v_cvt_pk_bf16_f32 v151, v151, v156
	v_cvt_pk_bf16_f32 v152, v152, v155
	v_cvt_pk_bf16_f32 v153, v153, v154
	v_cvt_pk_bf16_f32 v154, v186, v187
	v_cvt_pk_bf16_f32 v155, v188, v189
	v_cvt_pk_bf16_f32 v156, v220, v213
	v_cvt_pk_bf16_f32 v157, v214, v215
	v_cvt_pk_bf16_f32 v158, v216, v217
	v_cvt_pk_bf16_f32 v159, v218, v219
	v_cvt_pk_bf16_f32 v160, v221, v222
	v_cvt_pk_bf16_f32 v161, v223, v224
	s_nop 1
	v_permlane32_swap_b32_e32 v211, v212
	v_permlane32_swap_b32_e32 v146, v148
	v_permlane32_swap_b32_e32 v147, v149
	v_permlane32_swap_b32_e32 v150, v152
	v_permlane32_swap_b32_e32 v151, v153
	v_permlane32_swap_b32_e32 v154, v156
	v_permlane32_swap_b32_e32 v155, v157
	v_permlane32_swap_b32_e32 v158, v160
	v_permlane32_swap_b32_e32 v159, v161
	s_waitcnt vmcnt(0)
	ds_write_b128 v192, v[130:133] offset:16384
	ds_write_b128 v193, v[134:137] offset:16384
	ds_write_b128 v177, v[138:141] offset:49152
	ds_write_b128 v191, v[142:145] offset:49152
	s_cmp_gt_u32 s34, 60
	s_cselect_b64 s[2:3], -1, 0
	s_and_b64 vcc, exec, s[2:3]
	s_cbranch_vccnz .LBB0_1008
	v_add_co_u32_e32 v114, vcc, 0x19040000, v168
	s_nop 1
	v_addc_co_u32_e32 v115, vcc, 0, v169, vcc
	v_add_co_u32_e32 v118, vcc, 0x19088000, v168
	s_nop 1
	v_addc_co_u32_e32 v119, vcc, 0, v169, vcc
	v_add_co_u32_e32 v122, vcc, 0x1f660000, v166
	global_load_dwordx4 v[114:117], v[114:115], off
	s_nop 0
	global_load_dwordx4 v[118:121], v[118:119], off
	v_addc_co_u32_e32 v123, vcc, 0, v167, vcc
	v_add_co_u32_e32 v126, vcc, 0x1f66c000, v166
	s_nop 1
	v_addc_co_u32_e32 v127, vcc, 0, v167, vcc
	global_load_dwordx4 v[122:125], v[122:123], off
	s_nop 0
	global_load_dwordx4 v[126:129], v[126:127], off

; __device__ __forceinline__ void finishSM(f32x16& p0, f32x16& p1, float alpha, float& l_reg, bf16x8& pa0, bf16x8& pa1, bf16x8& pa2, bf16x8& pa3) {
; #pragma unroll
;   for (int r = 0; r < 16; ++r) p1[r] = __builtin_amdgcn_exp2f(p1[r]);
;   float ps = 0;
; #pragma unroll
;   for (int r = 0; r < 16; ++r) ps += p0[r];
; #pragma unroll
;   for (int r = 0; r < 16; ++r) ps += p1[r];
;   { auto rr = __builtin_amdgcn_permlane32_swap(__float_as_uint(ps), __float_as_uint(ps), false, false);
;     ps = __uint_as_float(rr[0]) + __uint_as_float(rr[1]); }
;   l_reg = l_reg * alpha + ps;
;   PK4(p0, 0, pa0); PK4(p0, 8, pa1); PK4(p1, 0, pa2); PK4(p1, 8, pa3);
; }
;   p0 = f32x16{}; p1 = f32x16{};
; #pragma unroll
;   for (int d0 = DLO; d0 < DHI; ++d0) { int cb = (d0 * 16 + hi * 8) * 2;
;     bf16x8 b0 = *reinterpret_cast<const bf16x8*>((const char*)Ks + KSWZ(r32, cb));
;     bf16x8 b1 = *reinterpret_cast<const bf16x8*>((const char*)Ks + KSWZ(32 + r32, cb));
;     p0 = __builtin_amdgcn_mfma_f32_32x32x16_bf16(b0, qr[d0], p0, 0, 0, 0);
;     p1 = __builtin_amdgcn_mfma_f32_32x32x16_bf16(b1, qr[d0], p1, 0, 0, 0); }
; }
; __device__ __forceinline__ int v_st(int k, int c) { const int kk = (k & ~0xC) | ((k & 4) << 1) | ((k & 8) >> 1); return ((kk >> 3) * 4 + (c >> 5)) * 512 + ((kk & 7) * 32 + (c & 31)) * 2; }
; __device__ __forceinline__ int v_rd_base(int lane) { return ((lane & 3) << 3) | (((lane >> 2) & 3) << 6) | (((lane >> 4) & 1) << 5) | (((lane >> 5) & 1) << 8); }
; template <int OFF> __device__ __forceinline__ s16x4 tr_read(int vb) {
;   s16x4 r; asm volatile("ds_read_b64_tr_b16 %0, %1 offset:%2" : "=&v"(r) : "v"(vb), "i"(OFF) : "memory"); return r;
; }
; template <int D0> __device__ __forceinline__ void pv_one(f32x16& od, int vb, bf16x8 pa0, bf16x8 pa1, bf16x8 pa2, bf16x8 pa3) {
; template <int DLO, int DHI>
; __device__ __forceinline__ void attn_dense_body(const int g_wave, const bf16* __restrict__ Qb, const bf16* __restrict__ Kh, const bf16* __restrict__ Vh,
;                                                 bf16* __restrict__ Ob, int ldo, char* lds) {
;     ...
;     SBAR(); qkt<DLO, DHI>(pB0, pB1, (bf16*)((char*)K_lds + SHM_K), qr, r32, hi);
;     finishSM(pA0, pA1, alA, l_reg, pa0, pa1, pa2, pa3); SBAR();
;     SLOAD(SO, (j + 2) * KVBLK); SBAR();
;     pv_d0(o, vb0, pa0, pa1, pa2, pa3); partialSM(pB0, pB1, m_reg, mnB, alB);
;     __syncthreads(); SWAIT(); SWRITE(0, SE);
.LBB0_1022:
	ds_read_b128 v[66:69], v177 offset:49152
	ds_read_b128 v[70:73], v177 offset:57344
	ds_read_b128 v[186:189], v194 offset:49152
	ds_read_b128 v[208:211], v194 offset:57344
	ds_read_b128 v[232:235], v195 offset:49152
	ds_read_b128 v[236:239], v195 offset:57344
	ds_read_b128 v[240:243], v196 offset:49152
	ds_read_b128 v[244:247], v196 offset:57344
	v_add_f32_e32 v146, 0, v161
	v_add_f32_e32 v146, v167, v146
	v_add_f32_e32 v146, v147, v146
	s_waitcnt lgkmcnt(6)
	v_mfma_f32_32x32x16_bf16 v[82:97], v[66:69], v[102:105], 0
	v_add_f32_e32 v146, v166, v146
	v_add_f32_e32 v146, v148, v146
	v_add_f32_e32 v146, v160, v146
	v_add_f32_e32 v146, v149, v146
	v_add_f32_e32 v146, v159, v146
	v_add_f32_e32 v146, v156, v146
	v_mfma_f32_32x32x16_bf16 v[66:81], v[70:73], v[102:105], 0
	v_add_f32_e32 v146, v158, v146
	v_add_f32_e32 v146, v154, v146
	v_add_f32_e32 v146, v157, v146
	v_exp_f32_e32 v142, v142
	v_add_f32_e32 v146, v152, v146
	v_exp_f32_e32 v143, v143
	v_add_f32_e32 v146, v155, v146
	s_waitcnt lgkmcnt(4)
	v_mfma_f32_32x32x16_bf16 v[82:97], v[186:189], v[98:101], v[82:97]
	v_exp_f32_e32 v140, v140
	v_add_f32_e32 v146, v151, v146
	v_exp_f32_e32 v141, v141
	v_add_f32_e32 v146, v153, v146
	v_exp_f32_e32 v134, v134
	v_add_f32_e32 v146, v142, v146
	v_exp_f32_e32 v135, v135
	v_mfma_f32_32x32x16_bf16 v[66:81], v[208:211], v[98:101], v[66:81]
	v_add_f32_e32 v146, v143, v146
	v_exp_f32_e32 v132, v132
	v_add_f32_e32 v146, v140, v146
	v_exp_f32_e32 v133, v133
	v_add_f32_e32 v146, v141, v146
	v_exp_f32_e32 v130, v130
	s_waitcnt lgkmcnt(2)
	v_mfma_f32_32x32x16_bf16 v[82:97], v[232:235], v[106:109], v[82:97]
	v_add_f32_e32 v146, v134, v146
	v_exp_f32_e32 v131, v131
	v_add_f32_e32 v146, v135, v146
	v_exp_f32_e32 v144, v144
	v_add_f32_e32 v146, v132, v146
	v_exp_f32_e32 v145, v145
	v_add_f32_e32 v146, v133, v146
	v_mfma_f32_32x32x16_bf16 v[66:81], v[236:239], v[106:109], v[66:81]
	v_exp_f32_e32 v138, v138
	v_add_f32_e32 v146, v130, v146
	v_exp_f32_e32 v139, v139
	v_add_f32_e32 v146, v131, v146
	v_exp_f32_e32 v136, v136
	v_add_f32_e32 v146, v144, v146
	s_waitcnt lgkmcnt(0)
	v_mfma_f32_32x32x16_bf16 v[82:97], v[240:243], v[110:113], v[82:97]
	v_exp_f32_e32 v137, v137
	v_add_f32_e32 v146, v145, v146
	v_add_f32_e32 v146, v138, v146
	v_add_f32_e32 v146, v139, v146
	v_add_f32_e32 v146, v136, v146
	v_add_f32_e32 v207, v137, v146
	v_cvt_pk_bf16_f32 v146, v161, v167
	v_mfma_f32_32x32x16_bf16 v[66:81], v[244:247], v[110:113], v[66:81]
	v_mov_b32_e32 v208, v207
	v_cvt_pk_bf16_f32 v147, v147, v166
	v_cvt_pk_bf16_f32 v148, v148, v160
	s_nop 1
	v_permlane32_swap_b32_e32 v207, v208
	v_cvt_pk_bf16_f32 v149, v149, v159
	v_permlane32_swap_b32_e32 v146, v148
	v_cvt_pk_bf16_f32 v156, v156, v158
	v_cvt_pk_bf16_f32 v157, v154, v157
	v_cvt_pk_bf16_f32 v158, v152, v155
	v_cvt_pk_bf16_f32 v159, v151, v153
	v_cvt_pk_bf16_f32 v152, v142, v143
	v_cvt_pk_bf16_f32 v153, v140, v141
	v_cvt_pk_bf16_f32 v154, v134, v135
	v_cvt_pk_bf16_f32 v155, v132, v133
	v_cvt_pk_bf16_f32 v186, v130, v131
	v_cvt_pk_bf16_f32 v187, v144, v145
	v_cvt_pk_bf16_f32 v188, v138, v139
	v_cvt_pk_bf16_f32 v189, v136, v137
	v_permlane32_swap_b32_e32 v147, v149
	v_permlane32_swap_b32_e32 v156, v158
	v_permlane32_swap_b32_e32 v157, v159
	v_permlane32_swap_b32_e32 v152, v154
	v_permlane32_swap_b32_e32 v153, v155
	v_permlane32_swap_b32_e32 v186, v188
	v_permlane32_swap_b32_e32 v187, v189
	s_waitcnt vmcnt(0)
	ds_write_b128 v192, v[114:117]
	ds_write_b128 v193, v[118:121]
	ds_write_b128 v190, v[122:125] offset:32768
	ds_write_b128 v191, v[126:129] offset:32768
	v_lshl_add_u64 v[168:169], v[164:165], 0, v[0:1]
	s_mov_b32 s1, 0x18fb0000
	v_add_co_u32_e32 v130, vcc, s1, v168
	s_mov_b32 s1, 0x18ff8000
	s_nop 0
	v_addc_co_u32_e32 v131, vcc, 0, v169, vcc
	v_add_co_u32_e32 v134, vcc, s1, v168
	v_lshl_add_u64 v[166:167], v[162:163], 0, v[0:1]
	s_nop 0
	v_addc_co_u32_e32 v135, vcc, 0, v169, vcc
	s_mov_b32 s1, 0x1f648000
	v_add_co_u32_e32 v138, vcc, s1, v166
	s_mov_b32 s1, 0x1f654000
	s_nop 0
	v_addc_co_u32_e32 v139, vcc, 0, v167, vcc
	v_add_co_u32_e32 v142, vcc, s1, v166
	global_load_dwordx4 v[130:133], v[130:131], off
	s_nop 0
	global_load_dwordx4 v[134:137], v[134:135], off
	v_addc_co_u32_e32 v143, vcc, 0, v167, vcc
	global_load_dwordx4 v[138:141], v[138:139], off
	s_nop 0
	global_load_dwordx4 v[142:145], v[142:143], off
	ds_read_b64_tr_b16 v[210:211], v176 offset:0
	ds_read_b64_tr_b16 v[212:213], v176 offset:0x800
	ds_read_b64_tr_b16 v[214:215], v176 offset:0x1000
	ds_read_b64_tr_b16 v[216:217], v176 offset:0x1800
	ds_read_b64_tr_b16 v[218:219], v176 offset:0x2000
	ds_read_b64_tr_b16 v[220:221], v176 offset:0x2800
	ds_read_b64_tr_b16 v[222:223], v176 offset:0x3000
	ds_read_b64_tr_b16 v[224:225], v176 offset:0x3800
	s_waitcnt lgkmcnt(4)
	s_nop 0
	v_mfma_f32_32x32x16_bf16 v[2:17], v[146:149], v[210:213], v[2:17]
	ds_read_b64_tr_b16 v[210:211], v176 offset:0x200
	ds_read_b64_tr_b16 v[212:213], v176 offset:0xa00
	v_mfma_f32_32x32x16_bf16 v[2:17], v[156:159], v[214:217], v[2:17]
	ds_read_b64_tr_b16 v[214:215], v176 offset:0x1200
	ds_read_b64_tr_b16 v[216:217], v176 offset:0x1a00
	s_waitcnt lgkmcnt(4)
	v_mfma_f32_32x32x16_bf16 v[2:17], v[152:155], v[218:221], v[2:17]
	ds_read_b64_tr_b16 v[218:219], v176 offset:0x2200
	ds_read_b64_tr_b16 v[220:221], v176 offset:0x2a00
	v_mfma_f32_32x32x16_bf16 v[2:17], v[186:189], v[222:225], v[2:17]
	ds_read_b64_tr_b16 v[222:223], v176 offset:0x3200
	ds_read_b64_tr_b16 v[224:225], v176 offset:0x3a00
	s_waitcnt lgkmcnt(4)
; #define SBAR() __builtin_amdgcn_sched_barrier(0)
; __device__ __forceinline__ void partialSM(f32x16& p0, f32x16& p1, float& m_reg, float& mn, float& alpha) {
;   constexpr float C = SCALE * 1.4426950408889634f;
;   float pmax = p0[0];
; #pragma unroll
;   for (int r = 1; r < 16; ++r) pmax = fmaxf(pmax, p0[r]);
; #pragma unroll
;   for (int r = 0; r < 16; ++r) pmax = fmaxf(pmax, p1[r]);
;   { auto rr = __builtin_amdgcn_permlane32_swap(__float_as_uint(pmax), __float_as_uint(pmax), false, false);
;     pmax = fmaxf(__uint_as_float(rr[0]), __uint_as_float(rr[1])); }
;   if (__builtin_expect(__all(pmax - m_reg <= THR / SCALE), 1)) { mn = m_reg; alpha = 1.f; }
;   else { mn = fmaxf(m_reg, pmax); alpha = __builtin_amdgcn_exp2f((m_reg - mn) * C); m_reg = mn; }
; template <int D0> __device__ __forceinline__ void pv_one(f32x16& od, int vb, bf16x8 pa0, bf16x8 pa1, bf16x8 pa2, bf16x8 pa3) {
;   const s16x4 l0 = tr_read<v_rd_off(D0, 0, 0)>(vb), h0 = tr_read<v_rd_off(D0, 0, 1)>(vb), l1 = tr_read<v_rd_off(D0, 1, 0)>(vb), h1 = tr_read<v_rd_off(D0, 1, 1)>(vb);
;   const s16x4 l2 = tr_read<v_rd_off(D0, 2, 0)>(vb), h2 = tr_read<v_rd_off(D0, 2, 1)>(vb), l3 = tr_read<v_rd_off(D0, 3, 0)>(vb), h3 = tr_read<v_rd_off(D0, 3, 1)>(vb);
;   asm volatile("s_waitcnt lgkmcnt(0)" ::: "memory"); SBAR();
;     ...
;   od = __builtin_amdgcn_mfma_f32_32x32x16_bf16(pa0, PK(l0, h0), od, 0, 0, 0);
;   od = __builtin_amdgcn_mfma_f32_32x32x16_bf16(pa1, PK(l1, h1), od, 0, 0, 0);
;   od = __builtin_amdgcn_mfma_f32_32x32x16_bf16(pa2, PK(l2, h2), od, 0, 0, 0);
;   od = __builtin_amdgcn_mfma_f32_32x32x16_bf16(pa3, PK(l3, h3), od, 0, 0, 0);
;     ...
; }
; __device__ __forceinline__ void pv_d0(f32x16* o, int vb, bf16x8 pa0, bf16x8 pa1, bf16x8 pa2, bf16x8 pa3) {
;   pv_one<0>(o[0], vb, pa0, pa1, pa2, pa3); pv_one<1>(o[1], vb, pa0, pa1, pa2, pa3); pv_one<2>(o[2], vb, pa0, pa1, pa2, pa3); pv_one<3>(o[3], vb, pa0, pa1, pa2, pa3);
	v_mfma_f32_32x32x16_bf16 v[50:65], v[146:149], v[210:213], v[50:65]
	ds_read_b64_tr_b16 v[210:211], v176 offset:0x400
	ds_read_b64_tr_b16 v[212:213], v176 offset:0xc00
	v_mfma_f32_32x32x16_bf16 v[50:65], v[156:159], v[214:217], v[50:65]
	ds_read_b64_tr_b16 v[214:215], v176 offset:0x1400
	ds_read_b64_tr_b16 v[216:217], v176 offset:0x1c00
	s_waitcnt lgkmcnt(4)
	v_mfma_f32_32x32x16_bf16 v[50:65], v[152:155], v[218:221], v[50:65]
	ds_read_b64_tr_b16 v[218:219], v176 offset:0x2400
	ds_read_b64_tr_b16 v[220:221], v176 offset:0x2c00
	v_mfma_f32_32x32x16_bf16 v[50:65], v[186:189], v[222:225], v[50:65]
	ds_read_b64_tr_b16 v[222:223], v176 offset:0x3400
	ds_read_b64_tr_b16 v[224:225], v176 offset:0x3c00
	s_waitcnt lgkmcnt(4)
	v_mfma_f32_32x32x16_bf16 v[34:49], v[146:149], v[210:213], v[34:49]
	ds_read_b64_tr_b16 v[210:211], v176 offset:0x600
	ds_read_b64_tr_b16 v[212:213], v176 offset:0xe00
	v_mfma_f32_32x32x16_bf16 v[34:49], v[156:159], v[214:217], v[34:49]
	ds_read_b64_tr_b16 v[214:215], v176 offset:0x1600
	ds_read_b64_tr_b16 v[216:217], v176 offset:0x1e00
	s_waitcnt lgkmcnt(4)
	v_mfma_f32_32x32x16_bf16 v[34:49], v[152:155], v[218:221], v[34:49]
	ds_read_b64_tr_b16 v[218:219], v176 offset:0x2600
	ds_read_b64_tr_b16 v[220:221], v176 offset:0x2e00
	v_mfma_f32_32x32x16_bf16 v[34:49], v[186:189], v[222:225], v[34:49]
	ds_read_b64_tr_b16 v[222:223], v176 offset:0x3600
	ds_read_b64_tr_b16 v[224:225], v176 offset:0x3e00
	s_waitcnt lgkmcnt(4)
	v_mfma_f32_32x32x16_bf16 v[18:33], v[146:149], v[210:213], v[18:33]
	v_max_f32_e32 v146, v83, v83
	v_max_f32_e32 v147, v82, v82
	v_max_f32_e32 v146, v147, v146
	v_max3_f32 v146, v146, v84, v85
	v_max3_f32 v146, v146, v86, v87
	v_max3_f32 v146, v146, v88, v89
	v_max3_f32 v146, v146, v90, v91
	v_max3_f32 v146, v146, v92, v93
	v_max3_f32 v146, v146, v94, v95
	v_mfma_f32_32x32x16_bf16 v[18:33], v[156:159], v[214:217], v[18:33]
	v_max3_f32 v146, v146, v96, v97
	v_max3_f32 v146, v146, v66, v67
	v_max3_f32 v146, v146, v68, v69
	v_max3_f32 v146, v146, v70, v71
	v_max3_f32 v146, v146, v72, v73
	v_max3_f32 v146, v146, v74, v75
	v_max3_f32 v146, v146, v76, v77
	v_max3_f32 v146, v146, v78, v79
	s_waitcnt lgkmcnt(0)
	v_mfma_f32_32x32x16_bf16 v[18:33], v[152:155], v[218:221], v[18:33]
	v_max3_f32 v146, v146, v80, v81
	v_mov_b32_e32 v147, v146
	s_nop 1
	v_permlane32_swap_b32_e32 v146, v147
	v_max_f32_e32 v147, v147, v147
	v_max_f32_e32 v146, v146, v146
	v_max_f32_e32 v146, v146, v147
	v_sub_f32_e32 v147, v146, v150
	v_cmp_ge_f32_e32 vcc, s63, v147
	v_max_f32_e32 v147, v150, v150
	v_max_f32_e32 v146, v147, v146
	v_mfma_f32_32x32x16_bf16 v[18:33], v[186:189], v[222:225], v[18:33]
	v_sub_f32_e32 v147, v150, v146
	v_mul_f32_e32 v147, 0x3e0293ee, v147
	v_exp_f32_e32 v147, v147
	s_cmp_eq_u64 vcc, exec
	s_cselect_b64 s[8:9], -1, 0
	s_waitcnt vmcnt(4)
	v_cndmask_b32_e64 v209, v147, 1.0, s[8:9]
	v_cmp_gt_f32_e32 vcc, 1.0, v209
	s_cbranch_vccz .LBB0_1026
	s_and_saveexec_b64 s[2:3], s[6:7]
	ds_write_b32 v173, v209 offset:128
	s_or_b64 exec, exec, s[2:3]
	s_waitcnt lgkmcnt(0)
	v_add_u32_e32 v147, s15, v172
	ds_read_b128 v[152:155], v147 offset:224
	ds_read_b128 v[156:159], v147 offset:192
	ds_read_b128 v[186:189], v147 offset:160
	ds_read_b128 v[210:213], v147 offset:128
	s_waitcnt lgkmcnt(3)
	v_pk_mul_f32 v[14:15], v[14:15], v[152:153]
	s_waitcnt lgkmcnt(2)
	v_pk_mul_f32 v[10:11], v[10:11], v[156:157]
	s_waitcnt lgkmcnt(1)
	v_pk_mul_f32 v[6:7], v[6:7], v[186:187]
	v_pk_mul_f32 v[16:17], v[16:17], v[154:155]
	v_pk_mul_f32 v[12:13], v[12:13], v[158:159]
	v_pk_mul_f32 v[8:9], v[8:9], v[188:189]
	s_waitcnt lgkmcnt(0)
	v_pk_mul_f32 v[4:5], v[4:5], v[212:213]
	v_pk_mul_f32 v[2:3], v[2:3], v[210:211]
	v_pk_mul_f32 v[62:63], v[62:63], v[152:153]
	v_pk_mul_f32 v[58:59], v[58:59], v[156:157]
	v_pk_mul_f32 v[54:55], v[54:55], v[186:187]
	v_pk_mul_f32 v[64:65], v[64:65], v[154:155]
	v_pk_mul_f32 v[60:61], v[60:61], v[158:159]
	v_pk_mul_f32 v[56:57], v[56:57], v[188:189]
	v_pk_mul_f32 v[52:53], v[52:53], v[212:213]
	v_pk_mul_f32 v[50:51], v[50:51], v[210:211]
	v_pk_mul_f32 v[46:47], v[46:47], v[152:153]
	v_pk_mul_f32 v[42:43], v[42:43], v[156:157]
	v_pk_mul_f32 v[38:39], v[38:39], v[186:187]
	v_pk_mul_f32 v[48:49], v[48:49], v[154:155]
	v_pk_mul_f32 v[44:45], v[44:45], v[158:159]
	v_pk_mul_f32 v[40:41], v[40:41], v[188:189]
	v_pk_mul_f32 v[36:37], v[36:37], v[212:213]
	v_pk_mul_f32 v[34:35], v[34:35], v[210:211]
	v_pk_mul_f32 v[30:31], v[30:31], v[152:153]
	v_pk_mul_f32 v[26:27], v[26:27], v[156:157]
	v_pk_mul_f32 v[22:23], v[22:23], v[186:187]
	v_pk_mul_f32 v[32:33], v[32:33], v[154:155]
	v_pk_mul_f32 v[28:29], v[28:29], v[158:159]
	v_pk_mul_f32 v[24:25], v[24:25], v[188:189]
	v_pk_mul_f32 v[20:21], v[20:21], v[212:213]
	v_pk_mul_f32 v[18:19], v[18:19], v[210:211]
; #define SBAR() __builtin_amdgcn_sched_barrier(0)
; __device__ __forceinline__ void partialSM(f32x16& p0, f32x16& p1, float& m_reg, float& mn, float& alpha) {
;     ...
;   float mnC = -mn * C;
; #pragma unroll
;   for (int r = 0; r < 16; ++r) p0[r] = fmaf(p0[r], C, mnC);
; #pragma unroll
;   for (int r = 0; r < 16; ++r) p1[r] = fmaf(p1[r], C, mnC);
; #pragma unroll
;   for (int r = 0; r < 16; ++r) p0[r] = __builtin_amdgcn_exp2f(p0[r]);
; }
; __device__ __forceinline__ void finishSM(f32x16& p0, f32x16& p1, float alpha, float& l_reg, bf16x8& pa0, bf16x8& pa1, bf16x8& pa2, bf16x8& pa3) {
; #pragma unroll
;   for (int r = 0; r < 16; ++r) p1[r] = __builtin_amdgcn_exp2f(p1[r]);
;   float ps = 0;
; #pragma unroll
;   for (int r = 0; r < 16; ++r) ps += p0[r];
; #pragma unroll
;   for (int r = 0; r < 16; ++r) ps += p1[r];
;   { auto rr = __builtin_amdgcn_permlane32_swap(__float_as_uint(ps), __float_as_uint(ps), false, false);
;     ps = __uint_as_float(rr[0]) + __uint_as_float(rr[1]); }
;   l_reg = l_reg * alpha + ps;
;   PK4(p0, 0, pa0); PK4(p0, 8, pa1); PK4(p1, 0, pa2); PK4(p1, 8, pa3);
; }
;   p0 = f32x16{}; p1 = f32x16{};
; #pragma unroll
;   for (int d0 = DLO; d0 < DHI; ++d0) { int cb = (d0 * 16 + hi * 8) * 2;
;     bf16x8 b0 = *reinterpret_cast<const bf16x8*>((const char*)Ks + KSWZ(r32, cb));
;     bf16x8 b1 = *reinterpret_cast<const bf16x8*>((const char*)Ks + KSWZ(32 + r32, cb));
; template <int DLO, int DHI>
; __device__ __forceinline__ void attn_dense_body(const int g_wave, const bf16* __restrict__ Qb, const bf16* __restrict__ Kh, const bf16* __restrict__ Vh,
;                                                 bf16* __restrict__ Ob, int ldo, char* lds) {
;     ...
;     SBAR(); qkt<DLO, DHI>(pB0, pB1, (bf16*)((char*)K_lds + SHM_K), qr, r32, hi);
;     finishSM(pA0, pA1, alA, l_reg, pa0, pa1, pa2, pa3); SBAR();
;     SLOAD(SO, (j + 2) * KVBLK); SBAR();
;     pv_d0(o, vb0, pa0, pa1, pa2, pa3); partialSM(pB0, pB1, m_reg, mnB, alB);
;     __syncthreads(); SWAIT(); SWRITE(0, SE);
;     RESC(alB); __syncthreads();
;     SBAR(); qkt<DLO, DHI>(pA0, pA1, K_lds, qr, r32, hi);
;     finishSM(pB0, pB1, alB, l_reg, pa0, pa1, pa2, pa3); SBAR();
;     if (j + 3 < NT) SLOAD(SE, (j + 3) * KVBLK); SBAR();
;     pv_d0(o, vb0 + (int)SHM_V, pa0, pa1, pa2, pa3); partialSM(pA0, pA1, m_reg, mnA, alA);
;     __syncthreads(); SWAIT(); SWRITE(1, SO);
;     RESC(alA); __syncthreads();
.LBB0_1026:
	v_cndmask_b32_e64 v210, v146, v150, s[8:9]
	v_mul_f32_e32 v211, 0xbe0293ee, v210
	v_fmamk_f32 v82, v82, 0x3e0293ee, v211
	v_fmamk_f32 v83, v83, 0x3e0293ee, v211
	v_fmamk_f32 v84, v84, 0x3e0293ee, v211
	v_fmamk_f32 v85, v85, 0x3e0293ee, v211
	v_fmamk_f32 v86, v86, 0x3e0293ee, v211
	v_fmamk_f32 v87, v87, 0x3e0293ee, v211
	v_fmamk_f32 v88, v88, 0x3e0293ee, v211
	v_fmamk_f32 v89, v89, 0x3e0293ee, v211
	v_fmamk_f32 v90, v90, 0x3e0293ee, v211
	v_fmamk_f32 v91, v91, 0x3e0293ee, v211
	v_fmamk_f32 v92, v92, 0x3e0293ee, v211
	v_fmamk_f32 v93, v93, 0x3e0293ee, v211
	v_fmamk_f32 v94, v94, 0x3e0293ee, v211
	v_fmamk_f32 v95, v95, 0x3e0293ee, v211
	v_fmamk_f32 v96, v96, 0x3e0293ee, v211
	v_fmamk_f32 v97, v97, 0x3e0293ee, v211
	v_exp_f32_e32 v146, v82
	v_exp_f32_e32 v161, v83
	v_exp_f32_e32 v147, v84
	v_exp_f32_e32 v160, v85
	v_exp_f32_e32 v148, v86
	v_exp_f32_e32 v159, v87
	v_exp_f32_e32 v149, v88
	v_exp_f32_e32 v158, v89
	v_exp_f32_e32 v150, v90
	v_exp_f32_e32 v157, v91
	v_exp_f32_e32 v151, v92
	v_exp_f32_e32 v156, v93
	v_exp_f32_e32 v152, v94
	v_exp_f32_e32 v155, v95
	v_exp_f32_e32 v153, v96
	v_exp_f32_e32 v154, v97
	v_fmamk_f32 v220, v66, 0x3e0293ee, v211
	v_fmamk_f32 v221, v67, 0x3e0293ee, v211
	v_fmamk_f32 v222, v68, 0x3e0293ee, v211
	v_fmamk_f32 v223, v69, 0x3e0293ee, v211
	v_fmamk_f32 v224, v70, 0x3e0293ee, v211
	v_fmamk_f32 v213, v71, 0x3e0293ee, v211
	v_fmamk_f32 v214, v72, 0x3e0293ee, v211
	v_fmamk_f32 v215, v73, 0x3e0293ee, v211
	v_fmamk_f32 v216, v74, 0x3e0293ee, v211
	v_fmamk_f32 v217, v75, 0x3e0293ee, v211
	v_fmamk_f32 v218, v76, 0x3e0293ee, v211
	v_fmamk_f32 v219, v77, 0x3e0293ee, v211
	v_fmamk_f32 v212, v78, 0x3e0293ee, v211
	v_fmamk_f32 v225, v79, 0x3e0293ee, v211
	v_fmamk_f32 v226, v80, 0x3e0293ee, v211
	v_fmac_f32_e32 v211, 0x3e0293ee, v81
	v_xor_b32_e32 v177, 0x10000, v177
	v_xor_b32_e32 v194, 0x10000, v194
	v_xor_b32_e32 v195, 0x10000, v195
	v_xor_b32_e32 v196, 0x10000, v196
	s_waitcnt lgkmcnt(0)
	s_barrier
	ds_read_b128 v[66:69], v177 offset:32768
	ds_read_b128 v[70:73], v177 offset:40960
	ds_read_b128 v[232:235], v194 offset:32768
	ds_read_b128 v[236:239], v194 offset:40960
	ds_read_b128 v[240:243], v195 offset:32768
	ds_read_b128 v[244:247], v195 offset:40960
	ds_read_b128 v[248:251], v196 offset:32768
	ds_read_b128 v[114:117], v196 offset:40960
	v_exp_f32_e32 v213, v213
	v_exp_f32_e32 v214, v214
	s_waitcnt lgkmcnt(6)
	v_mfma_f32_32x32x16_bf16 v[82:97], v[66:69], v[102:105], 0
	v_exp_f32_e32 v215, v215
	v_exp_f32_e32 v216, v216
	v_exp_f32_e32 v217, v217
	v_exp_f32_e32 v218, v218
	v_exp_f32_e32 v219, v219
	v_mfma_f32_32x32x16_bf16 v[66:81], v[70:73], v[102:105], 0
	s_waitcnt lgkmcnt(4)
	v_mfma_f32_32x32x16_bf16 v[82:97], v[232:235], v[98:101], v[82:97]
	v_mfma_f32_32x32x16_bf16 v[66:81], v[236:239], v[98:101], v[66:81]
	s_waitcnt lgkmcnt(2)
	v_mfma_f32_32x32x16_bf16 v[82:97], v[240:243], v[106:109], v[82:97]
	v_mfma_f32_32x32x16_bf16 v[66:81], v[244:247], v[106:109], v[66:81]
	s_waitcnt lgkmcnt(0)
	v_mfma_f32_32x32x16_bf16 v[82:97], v[248:251], v[110:113], v[82:97]
	v_exp_f32_e32 v186, v220
	v_exp_f32_e32 v220, v224
	v_exp_f32_e32 v224, v211
	v_add_f32_e32 v211, 0, v146
	v_add_f32_e32 v211, v161, v211
	v_add_f32_e32 v211, v147, v211
	v_add_f32_e32 v211, v160, v211
	v_add_f32_e32 v211, v148, v211
	v_add_f32_e32 v211, v159, v211
	v_add_f32_e32 v211, v149, v211
	v_add_f32_e32 v211, v158, v211
	v_add_f32_e32 v211, v150, v211
	v_add_f32_e32 v211, v157, v211
	v_add_f32_e32 v211, v151, v211
	v_add_f32_e32 v211, v156, v211
	v_add_f32_e32 v211, v152, v211
	v_exp_f32_e32 v187, v221
	v_add_f32_e32 v211, v155, v211
	v_exp_f32_e32 v188, v222
	v_add_f32_e32 v211, v153, v211
	v_exp_f32_e32 v189, v223
	v_add_f32_e32 v211, v154, v211
	v_add_f32_e32 v211, v186, v211
	v_add_f32_e32 v211, v187, v211
	v_add_f32_e32 v211, v188, v211
	v_add_f32_e32 v211, v189, v211
	v_add_f32_e32 v211, v220, v211
	v_add_f32_e32 v211, v213, v211
	v_add_f32_e32 v211, v214, v211
	v_add_f32_e32 v211, v215, v211
	v_exp_f32_e32 v221, v212
	v_add_f32_e32 v211, v216, v211
	v_exp_f32_e32 v222, v225
	v_add_f32_e32 v211, v217, v211
	v_mfma_f32_32x32x16_bf16 v[66:81], v[114:117], v[110:113], v[66:81]
	v_exp_f32_e32 v223, v226
	v_add_f32_e32 v211, v218, v211
	v_add_f32_e32 v211, v219, v211
	v_add_f32_e32 v211, v221, v211
	v_add_f32_e32 v211, v222, v211
	v_add_f32_e32 v211, v223, v211
	v_add_f32_e32 v211, v224, v211
	v_mov_b32_e32 v212, v211
	v_cvt_pk_bf16_f32 v146, v146, v161
	v_cvt_pk_bf16_f32 v147, v147, v160
	v_cvt_pk_bf16_f32 v148, v148, v159
	v_cvt_pk_bf16_f32 v149, v149, v158
	v_cvt_pk_bf16_f32 v150, v150, v157
	v_cvt_pk_bf16_f32 v151, v151, v156
	v_cvt_pk_bf16_f32 v152, v152, v155
	v_cvt_pk_bf16_f32 v153, v153, v154
	v_cvt_pk_bf16_f32 v154, v186, v187
	v_cvt_pk_bf16_f32 v155, v188, v189
	v_cvt_pk_bf16_f32 v156, v220, v213
	v_cvt_pk_bf16_f32 v157, v214, v215
	v_cvt_pk_bf16_f32 v158, v216, v217
	v_cvt_pk_bf16_f32 v159, v218, v219
	v_cvt_pk_bf16_f32 v160, v221, v222
	v_cvt_pk_bf16_f32 v161, v223, v224
	s_nop 1
	v_permlane32_swap_b32_e32 v211, v212
	v_permlane32_swap_b32_e32 v146, v148
	v_permlane32_swap_b32_e32 v147, v149
	v_permlane32_swap_b32_e32 v150, v152
	v_permlane32_swap_b32_e32 v151, v153
	v_permlane32_swap_b32_e32 v154, v156
	v_permlane32_swap_b32_e32 v155, v157
	v_permlane32_swap_b32_e32 v158, v160
	v_permlane32_swap_b32_e32 v159, v161
	s_waitcnt vmcnt(0)
	ds_write_b128 v192, v[130:133] offset:16384
	ds_write_b128 v193, v[134:137] offset:16384
	ds_write_b128 v190, v[138:141] offset:49152
	ds_write_b128 v191, v[142:145] offset:49152
	s_cmp_gt_u32 s34, 60
	s_cselect_b64 s[2:3], -1, 0
	s_and_b64 vcc, exec, s[2:3]
	s_cbranch_vccnz .LBB0_1028
	v_add_co_u32_e32 v114, vcc, 0x19040000, v168
	s_nop 1
	v_addc_co_u32_e32 v115, vcc, 0, v169, vcc
	v_add_co_u32_e32 v118, vcc, 0x19088000, v168
	s_nop 1
	v_addc_co_u32_e32 v119, vcc, 0, v169, vcc
	v_add_co_u32_e32 v122, vcc, 0x1f660000, v166
	global_load_dwordx4 v[114:117], v[114:115], off
	s_nop 0
	global_load_dwordx4 v[118:121], v[118:119], off
	v_addc_co_u32_e32 v123, vcc, 0, v167, vcc
	v_add_co_u32_e32 v126, vcc, 0x1f66c000, v166
	s_nop 1
	v_addc_co_u32_e32 v127, vcc, 0, v167, vcc
	global_load_dwordx4 v[122:125], v[122:123], off
	s_nop 0
	global_load_dwordx4 v[126:129], v[126:127], off

; __device__ __forceinline__ void finishSM(f32x16& p0, f32x16& p1, float alpha, float& l_reg, bf16x8& pa0, bf16x8& pa1, bf16x8& pa2, bf16x8& pa3) {
; #pragma unroll
;   for (int r = 0; r < 16; ++r) p1[r] = __builtin_amdgcn_exp2f(p1[r]);
;   float ps = 0;
; #pragma unroll
;   for (int r = 0; r < 16; ++r) ps += p0[r];
; #pragma unroll
;   for (int r = 0; r < 16; ++r) ps += p1[r];
;   { auto rr = __builtin_amdgcn_permlane32_swap(__float_as_uint(ps), __float_as_uint(ps), false, false);
;     ps = __uint_as_float(rr[0]) + __uint_as_float(rr[1]); }
;   l_reg = l_reg * alpha + ps;
;   PK4(p0, 0, pa0); PK4(p0, 8, pa1); PK4(p1, 0, pa2); PK4(p1, 8, pa3);
; }
;   p0 = f32x16{}; p1 = f32x16{};
; #pragma unroll
;   for (int d0 = DLO; d0 < DHI; ++d0) { int cb = (d0 * 16 + hi * 8) * 2;
;     bf16x8 b0 = *reinterpret_cast<const bf16x8*>((const char*)Ks + KSWZ(r32, cb));
;     bf16x8 b1 = *reinterpret_cast<const bf16x8*>((const char*)Ks + KSWZ(32 + r32, cb));
;     p0 = __builtin_amdgcn_mfma_f32_32x32x16_bf16(b0, qr[d0], p0, 0, 0, 0);
;     p1 = __builtin_amdgcn_mfma_f32_32x32x16_bf16(b1, qr[d0], p1, 0, 0, 0); }
; }
; __device__ __forceinline__ int v_st(int k, int c) { const int kk = (k & ~0xC) | ((k & 4) << 1) | ((k & 8) >> 1); return ((kk >> 3) * 4 + (c >> 5)) * 512 + ((kk & 7) * 32 + (c & 31)) * 2; }
; __device__ __forceinline__ int v_rd_base(int lane) { return ((lane & 3) << 3) | (((lane >> 2) & 3) << 6) | (((lane >> 4) & 1) << 5) | (((lane >> 5) & 1) << 8); }
; template <int OFF> __device__ __forceinline__ s16x4 tr_read(int vb) {
;   s16x4 r; asm volatile("ds_read_b64_tr_b16 %0, %1 offset:%2" : "=&v"(r) : "v"(vb), "i"(OFF) : "memory"); return r;
; }
; template <int D0> __device__ __forceinline__ void pv_one(f32x16& od, int vb, bf16x8 pa0, bf16x8 pa1, bf16x8 pa2, bf16x8 pa3) {
; template <int DLO, int DHI>
; __device__ __forceinline__ void attn_dense_body(const int g_wave, const bf16* __restrict__ Qb, const bf16* __restrict__ Kh, const bf16* __restrict__ Vh,
;                                                 bf16* __restrict__ Ob, int ldo, char* lds) {
;     ...
;     SBAR(); qkt<DLO, DHI>(pB0, pB1, (bf16*)((char*)K_lds + SHM_K), qr, r32, hi);
;     finishSM(pA0, pA1, alA, l_reg, pa0, pa1, pa2, pa3); SBAR();
;     SLOAD(SO, (j + 2) * KVBLK); SBAR();
;     pv_d0(o, vb0, pa0, pa1, pa2, pa3); partialSM(pB0, pB1, m_reg, mnB, alB);
;     __syncthreads(); SWAIT(); SWRITE(0, SE);
.LBB0_1043:
	ds_read_b128 v[66:69], v218 offset:49152
	ds_read_b128 v[70:73], v218 offset:57344
	ds_read_b128 v[186:189], v225 offset:49152
	ds_read_b128 v[230:233], v225 offset:57344
	ds_read_b128 v[234:237], v224 offset:49152
	ds_read_b128 v[238:241], v224 offset:57344
	ds_read_b128 v[242:245], v222 offset:49152
	ds_read_b128 v[246:249], v222 offset:57344
	v_add_f32_e32 v162, 0, v177
	v_add_f32_e32 v162, v195, v162
	s_waitcnt lgkmcnt(6)
	v_mfma_f32_32x32x16_bf16 v[82:97], v[66:69], v[118:121], 0
	v_add_f32_e32 v162, v163, v162
	v_add_f32_e32 v162, v194, v162
	v_add_f32_e32 v162, v164, v162
	v_add_f32_e32 v162, v176, v162
	v_add_f32_e32 v162, v165, v162
	v_add_f32_e32 v162, v175, v162
	v_add_f32_e32 v162, v166, v162
	v_mfma_f32_32x32x16_bf16 v[66:81], v[70:73], v[118:121], 0
	v_add_f32_e32 v162, v174, v162
	v_add_f32_e32 v162, v167, v162
	v_add_f32_e32 v162, v173, v162
	v_exp_f32_e32 v158, v158
	v_add_f32_e32 v162, v168, v162
	v_exp_f32_e32 v159, v159
	v_add_f32_e32 v162, v172, v162
	s_waitcnt lgkmcnt(4)
	v_mfma_f32_32x32x16_bf16 v[82:97], v[186:189], v[110:113], v[82:97]
	v_exp_f32_e32 v156, v156
	v_add_f32_e32 v162, v169, v162
	v_exp_f32_e32 v157, v157
	v_add_f32_e32 v162, v171, v162
	v_exp_f32_e32 v150, v150
	v_add_f32_e32 v162, v158, v162
	v_exp_f32_e32 v151, v151
	v_mfma_f32_32x32x16_bf16 v[66:81], v[230:233], v[110:113], v[66:81]
	ds_read_b128 v[186:189], v220 offset:49152
	ds_read_b128 v[230:233], v220 offset:57344
	v_add_f32_e32 v162, v159, v162
	v_exp_f32_e32 v148, v148
	v_add_f32_e32 v162, v156, v162
	v_exp_f32_e32 v149, v149
	v_add_f32_e32 v162, v157, v162
	v_exp_f32_e32 v146, v146
	s_waitcnt lgkmcnt(4)
	v_mfma_f32_32x32x16_bf16 v[82:97], v[234:237], v[126:129], v[82:97]
	v_add_f32_e32 v162, v150, v162
	v_exp_f32_e32 v147, v147
	v_add_f32_e32 v162, v151, v162
	v_exp_f32_e32 v160, v160
	v_add_f32_e32 v162, v148, v162
	v_exp_f32_e32 v161, v161
	v_add_f32_e32 v162, v149, v162
	v_mfma_f32_32x32x16_bf16 v[66:81], v[238:241], v[126:129], v[66:81]
	ds_read_b128 v[234:237], v219 offset:49152
	ds_read_b128 v[238:241], v219 offset:57344
	v_exp_f32_e32 v154, v154
	v_add_f32_e32 v162, v146, v162
	v_exp_f32_e32 v155, v155
	v_add_f32_e32 v162, v147, v162
	v_exp_f32_e32 v152, v152
	v_add_f32_e32 v162, v160, v162
	s_waitcnt lgkmcnt(4)
	v_mfma_f32_32x32x16_bf16 v[82:97], v[242:245], v[122:125], v[82:97]
	v_exp_f32_e32 v153, v153
	v_add_f32_e32 v162, v161, v162
	v_add_f32_e32 v162, v154, v162
	v_add_f32_e32 v162, v155, v162
	v_add_f32_e32 v162, v152, v162
	v_add_f32_e32 v227, v153, v162
	v_mfma_f32_32x32x16_bf16 v[66:81], v[246:249], v[122:125], v[66:81]
	ds_read_b128 v[242:245], v221 offset:49152
	ds_read_b128 v[246:249], v221 offset:57344
	s_waitcnt lgkmcnt(4)
	v_mfma_f32_32x32x16_bf16 v[82:97], v[186:189], v[114:117], v[82:97]
	v_mfma_f32_32x32x16_bf16 v[66:81], v[230:233], v[114:117], v[66:81]
	ds_read_b128 v[186:189], v223 offset:49152
	ds_read_b128 v[230:233], v223 offset:57344
	s_waitcnt lgkmcnt(4)
	v_mfma_f32_32x32x16_bf16 v[82:97], v[234:237], v[106:109], v[82:97]
	v_mfma_f32_32x32x16_bf16 v[66:81], v[238:241], v[106:109], v[66:81]
	s_waitcnt lgkmcnt(2)
	v_mfma_f32_32x32x16_bf16 v[82:97], v[242:245], v[102:105], v[82:97]
	v_mfma_f32_32x32x16_bf16 v[66:81], v[246:249], v[102:105], v[66:81]
	v_cvt_pk_bf16_f32 v162, v177, v195
	v_cvt_pk_bf16_f32 v163, v163, v194
	v_cvt_pk_bf16_f32 v164, v164, v176
	v_cvt_pk_bf16_f32 v165, v165, v175
	v_cvt_pk_bf16_f32 v166, v166, v174
	v_cvt_pk_bf16_f32 v167, v167, v173
	s_waitcnt lgkmcnt(0)
	v_mfma_f32_32x32x16_bf16 v[82:97], v[186:189], v[98:101], v[82:97]
	v_mov_b32_e32 v228, v227
	s_nop 1
	v_permlane32_swap_b32_e32 v227, v228
	v_permlane32_swap_b32_e32 v162, v164
	v_cvt_pk_bf16_f32 v168, v168, v172
	v_cvt_pk_bf16_f32 v169, v169, v171
	v_mfma_f32_32x32x16_bf16 v[66:81], v[230:233], v[98:101], v[66:81]
	v_cvt_pk_bf16_f32 v172, v158, v159
	v_cvt_pk_bf16_f32 v173, v156, v157
	v_cvt_pk_bf16_f32 v174, v150, v151
	v_cvt_pk_bf16_f32 v175, v148, v149
	v_cvt_pk_bf16_f32 v230, v146, v147
	v_cvt_pk_bf16_f32 v231, v160, v161
	v_cvt_pk_bf16_f32 v232, v154, v155
	v_cvt_pk_bf16_f32 v233, v152, v153
	v_permlane32_swap_b32_e32 v163, v165
	v_permlane32_swap_b32_e32 v166, v168
	v_permlane32_swap_b32_e32 v167, v169
	v_permlane32_swap_b32_e32 v172, v174
	v_permlane32_swap_b32_e32 v173, v175
	v_permlane32_swap_b32_e32 v230, v232
	v_permlane32_swap_b32_e32 v231, v233
	s_waitcnt vmcnt(0)
	ds_write_b128 v216, v[130:133]
	ds_write_b128 v217, v[134:137]
	ds_write_b128 v214, v[138:141] offset:32768
	ds_write_b128 v215, v[142:145] offset:32768
	v_lshl_add_u64 v[196:197], v[192:193], 0, v[0:1]
	s_mov_b32 s1, 0x18fb0000
	v_add_co_u32_e32 v146, vcc, s1, v196
	s_mov_b32 s1, 0x18ff8000
	s_nop 0
	v_addc_co_u32_e32 v147, vcc, 0, v197, vcc
	v_add_co_u32_e32 v150, vcc, s1, v196
	v_lshl_add_u64 v[194:195], v[190:191], 0, v[0:1]
	s_nop 0
	v_addc_co_u32_e32 v151, vcc, 0, v197, vcc
	s_mov_b32 s1, 0x1f648000
	v_add_co_u32_e32 v154, vcc, s1, v194
	s_mov_b32 s1, 0x1f654000
	s_nop 0
	v_addc_co_u32_e32 v155, vcc, 0, v195, vcc
	v_add_co_u32_e32 v158, vcc, s1, v194
	global_load_dwordx4 v[146:149], v[146:147], off
	s_nop 0
	global_load_dwordx4 v[150:153], v[150:151], off
	v_addc_co_u32_e32 v159, vcc, 0, v195, vcc
	global_load_dwordx4 v[154:157], v[154:155], off
	s_nop 0
	global_load_dwordx4 v[158:161], v[158:159], off
	ds_read_b64_tr_b16 v[234:235], v213 offset:0
	ds_read_b64_tr_b16 v[236:237], v213 offset:0x800
	ds_read_b64_tr_b16 v[238:239], v213 offset:0x1000
	ds_read_b64_tr_b16 v[240:241], v213 offset:0x1800
	ds_read_b64_tr_b16 v[242:243], v213 offset:0x2000
	ds_read_b64_tr_b16 v[244:245], v213 offset:0x2800
	ds_read_b64_tr_b16 v[246:247], v213 offset:0x3000
	ds_read_b64_tr_b16 v[248:249], v213 offset:0x3800
	s_waitcnt lgkmcnt(4)
; #define SBAR() __builtin_amdgcn_sched_barrier(0)
; __device__ __forceinline__ void partialSM(f32x16& p0, f32x16& p1, float& m_reg, float& mn, float& alpha) {
;   constexpr float C = SCALE * 1.4426950408889634f;
;   float pmax = p0[0];
; #pragma unroll
;   for (int r = 1; r < 16; ++r) pmax = fmaxf(pmax, p0[r]);
; #pragma unroll
;   for (int r = 0; r < 16; ++r) pmax = fmaxf(pmax, p1[r]);
;   { auto rr = __builtin_amdgcn_permlane32_swap(__float_as_uint(pmax), __float_as_uint(pmax), false, false);
;     pmax = fmaxf(__uint_as_float(rr[0]), __uint_as_float(rr[1])); }
;   if (__builtin_expect(__all(pmax - m_reg <= THR / SCALE), 1)) { mn = m_reg; alpha = 1.f; }
;   else { mn = fmaxf(m_reg, pmax); alpha = __builtin_amdgcn_exp2f((m_reg - mn) * C); m_reg = mn; }
; template <int D0> __device__ __forceinline__ void pv_one(f32x16& od, int vb, bf16x8 pa0, bf16x8 pa1, bf16x8 pa2, bf16x8 pa3) {
;   const s16x4 l0 = tr_read<v_rd_off(D0, 0, 0)>(vb), h0 = tr_read<v_rd_off(D0, 0, 1)>(vb), l1 = tr_read<v_rd_off(D0, 1, 0)>(vb), h1 = tr_read<v_rd_off(D0, 1, 1)>(vb);
;   const s16x4 l2 = tr_read<v_rd_off(D0, 2, 0)>(vb), h2 = tr_read<v_rd_off(D0, 2, 1)>(vb), l3 = tr_read<v_rd_off(D0, 3, 0)>(vb), h3 = tr_read<v_rd_off(D0, 3, 1)>(vb);
;   asm volatile("s_waitcnt lgkmcnt(0)" ::: "memory"); SBAR();
;     ...
;   od = __builtin_amdgcn_mfma_f32_32x32x16_bf16(pa0, PK(l0, h0), od, 0, 0, 0);
;   od = __builtin_amdgcn_mfma_f32_32x32x16_bf16(pa1, PK(l1, h1), od, 0, 0, 0);
;   od = __builtin_amdgcn_mfma_f32_32x32x16_bf16(pa2, PK(l2, h2), od, 0, 0, 0);
;   od = __builtin_amdgcn_mfma_f32_32x32x16_bf16(pa3, PK(l3, h3), od, 0, 0, 0);
;     ...
; }
; __device__ __forceinline__ void pv_d0(f32x16* o, int vb, bf16x8 pa0, bf16x8 pa1, bf16x8 pa2, bf16x8 pa3) {
;   pv_one<0>(o[0], vb, pa0, pa1, pa2, pa3); pv_one<1>(o[1], vb, pa0, pa1, pa2, pa3); pv_one<2>(o[2], vb, pa0, pa1, pa2, pa3); pv_one<3>(o[3], vb, pa0, pa1, pa2, pa3);
	s_nop 0
	v_mfma_f32_32x32x16_bf16 v[2:17], v[162:165], v[234:237], v[2:17]
	ds_read_b64_tr_b16 v[234:235], v213 offset:0x200
	ds_read_b64_tr_b16 v[236:237], v213 offset:0xa00
	v_mfma_f32_32x32x16_bf16 v[2:17], v[166:169], v[238:241], v[2:17]
	ds_read_b64_tr_b16 v[238:239], v213 offset:0x1200
	ds_read_b64_tr_b16 v[240:241], v213 offset:0x1a00
	s_waitcnt lgkmcnt(4)
	v_mfma_f32_32x32x16_bf16 v[2:17], v[172:175], v[242:245], v[2:17]
	ds_read_b64_tr_b16 v[242:243], v213 offset:0x2200
	ds_read_b64_tr_b16 v[244:245], v213 offset:0x2a00
	v_mfma_f32_32x32x16_bf16 v[2:17], v[230:233], v[246:249], v[2:17]
	ds_read_b64_tr_b16 v[246:247], v213 offset:0x3200
	ds_read_b64_tr_b16 v[248:249], v213 offset:0x3a00
	s_waitcnt lgkmcnt(4)
	v_mfma_f32_32x32x16_bf16 v[50:65], v[162:165], v[234:237], v[50:65]
	ds_read_b64_tr_b16 v[234:235], v213 offset:0x400
	ds_read_b64_tr_b16 v[236:237], v213 offset:0xc00
	v_mfma_f32_32x32x16_bf16 v[50:65], v[166:169], v[238:241], v[50:65]
	ds_read_b64_tr_b16 v[238:239], v213 offset:0x1400
	ds_read_b64_tr_b16 v[240:241], v213 offset:0x1c00
	s_waitcnt lgkmcnt(4)
	v_mfma_f32_32x32x16_bf16 v[50:65], v[172:175], v[242:245], v[50:65]
	ds_read_b64_tr_b16 v[242:243], v213 offset:0x2400
	ds_read_b64_tr_b16 v[244:245], v213 offset:0x2c00
	v_mfma_f32_32x32x16_bf16 v[50:65], v[230:233], v[246:249], v[50:65]
	ds_read_b64_tr_b16 v[246:247], v213 offset:0x3400
	ds_read_b64_tr_b16 v[248:249], v213 offset:0x3c00
	s_waitcnt lgkmcnt(4)
	v_mfma_f32_32x32x16_bf16 v[34:49], v[162:165], v[234:237], v[34:49]
	ds_read_b64_tr_b16 v[234:235], v213 offset:0x600
	ds_read_b64_tr_b16 v[236:237], v213 offset:0xe00
	v_mfma_f32_32x32x16_bf16 v[34:49], v[166:169], v[238:241], v[34:49]
	ds_read_b64_tr_b16 v[238:239], v213 offset:0x1600
	ds_read_b64_tr_b16 v[240:241], v213 offset:0x1e00
	s_waitcnt lgkmcnt(4)
	v_mfma_f32_32x32x16_bf16 v[34:49], v[172:175], v[242:245], v[34:49]
	ds_read_b64_tr_b16 v[242:243], v213 offset:0x2600
	ds_read_b64_tr_b16 v[244:245], v213 offset:0x2e00
	v_mfma_f32_32x32x16_bf16 v[34:49], v[230:233], v[246:249], v[34:49]
	ds_read_b64_tr_b16 v[246:247], v213 offset:0x3600
	ds_read_b64_tr_b16 v[248:249], v213 offset:0x3e00
	s_waitcnt lgkmcnt(4)
	v_mfma_f32_32x32x16_bf16 v[18:33], v[162:165], v[234:237], v[18:33]
	v_max_f32_e32 v162, v83, v83
	v_max_f32_e32 v163, v82, v82
	v_max_f32_e32 v162, v163, v162
	v_max3_f32 v162, v162, v84, v85
	v_max3_f32 v162, v162, v86, v87
	v_max3_f32 v162, v162, v88, v89
	v_max3_f32 v162, v162, v90, v91
	v_max3_f32 v162, v162, v92, v93
	v_max3_f32 v162, v162, v94, v95
	v_mfma_f32_32x32x16_bf16 v[18:33], v[166:169], v[238:241], v[18:33]
	v_max3_f32 v162, v162, v96, v97
	v_max3_f32 v162, v162, v66, v67
	v_max3_f32 v162, v162, v68, v69
	v_max3_f32 v162, v162, v70, v71
	v_max3_f32 v162, v162, v72, v73
	v_max3_f32 v162, v162, v74, v75
	v_max3_f32 v162, v162, v76, v77
	v_max3_f32 v162, v162, v78, v79
	s_waitcnt lgkmcnt(0)
	v_mfma_f32_32x32x16_bf16 v[18:33], v[172:175], v[242:245], v[18:33]
	v_max3_f32 v162, v162, v80, v81
	v_mov_b32_e32 v163, v162
	s_nop 1
	v_permlane32_swap_b32_e32 v162, v163
	v_max_f32_e32 v163, v163, v163
	v_max_f32_e32 v162, v162, v162
	v_max_f32_e32 v162, v162, v163
	v_sub_f32_e32 v163, v162, v170
	v_cmp_ge_f32_e32 vcc, s63, v163
	v_max_f32_e32 v163, v170, v170
	v_max_f32_e32 v162, v163, v162
	v_mfma_f32_32x32x16_bf16 v[18:33], v[230:233], v[246:249], v[18:33]
	v_sub_f32_e32 v163, v170, v162
	v_mul_f32_e32 v163, 0x3e0293ee, v163
	v_exp_f32_e32 v163, v163
	s_cmp_eq_u64 vcc, exec
	s_cselect_b64 s[8:9], -1, 0
	s_waitcnt vmcnt(4)
	v_cndmask_b32_e64 v229, v163, 1.0, s[8:9]
	v_cmp_gt_f32_e32 vcc, 1.0, v229
	s_cbranch_vccz .LBB0_1047
	s_and_saveexec_b64 s[2:3], s[6:7]
	ds_write_b32 v210, v229 offset:128
	s_or_b64 exec, exec, s[2:3]
	s_waitcnt lgkmcnt(0)
	v_add_u32_e32 v163, s15, v209
	ds_read_b128 v[164:167], v163 offset:224
	ds_read_b128 v[172:175], v163 offset:192
	ds_read_b128 v[230:233], v163 offset:160
	ds_read_b128 v[234:237], v163 offset:128
	s_waitcnt lgkmcnt(3)
	v_pk_mul_f32 v[14:15], v[14:15], v[164:165]
	s_waitcnt lgkmcnt(2)
	v_pk_mul_f32 v[10:11], v[10:11], v[172:173]
	s_waitcnt lgkmcnt(1)
	v_pk_mul_f32 v[6:7], v[6:7], v[230:231]
	v_pk_mul_f32 v[16:17], v[16:17], v[166:167]
	v_pk_mul_f32 v[12:13], v[12:13], v[174:175]
	v_pk_mul_f32 v[8:9], v[8:9], v[232:233]
	s_waitcnt lgkmcnt(0)
	v_pk_mul_f32 v[4:5], v[4:5], v[236:237]
	v_pk_mul_f32 v[2:3], v[2:3], v[234:235]
	v_pk_mul_f32 v[62:63], v[62:63], v[164:165]
	v_pk_mul_f32 v[58:59], v[58:59], v[172:173]
	v_pk_mul_f32 v[54:55], v[54:55], v[230:231]
	v_pk_mul_f32 v[64:65], v[64:65], v[166:167]
	v_pk_mul_f32 v[60:61], v[60:61], v[174:175]
	v_pk_mul_f32 v[56:57], v[56:57], v[232:233]
	v_pk_mul_f32 v[52:53], v[52:53], v[236:237]
	v_pk_mul_f32 v[50:51], v[50:51], v[234:235]
	v_pk_mul_f32 v[46:47], v[46:47], v[164:165]
	v_pk_mul_f32 v[42:43], v[42:43], v[172:173]
	v_pk_mul_f32 v[38:39], v[38:39], v[230:231]
	v_pk_mul_f32 v[48:49], v[48:49], v[166:167]
	v_pk_mul_f32 v[44:45], v[44:45], v[174:175]
	v_pk_mul_f32 v[40:41], v[40:41], v[232:233]
	v_pk_mul_f32 v[36:37], v[36:37], v[236:237]
	v_pk_mul_f32 v[34:35], v[34:35], v[234:235]
	v_pk_mul_f32 v[30:31], v[30:31], v[164:165]
	v_pk_mul_f32 v[26:27], v[26:27], v[172:173]
	v_pk_mul_f32 v[22:23], v[22:23], v[230:231]
	v_pk_mul_f32 v[32:33], v[32:33], v[166:167]
	v_pk_mul_f32 v[28:29], v[28:29], v[174:175]
	v_pk_mul_f32 v[24:25], v[24:25], v[232:233]
	v_pk_mul_f32 v[20:21], v[20:21], v[236:237]
	v_pk_mul_f32 v[18:19], v[18:19], v[234:235]
; #define SWRITE(b, i) do { *(bf16x8*)((char*)V_lds + (b) * SHM_V + vst0) = sr_[i].vs0;          \
;     *(bf16x8*)((char*)V_lds + (b) * SHM_V + vst1) = sr_[i].vs1; int kc = sc * 2;               \
;     *(bf16x8*)((char*)K_lds + (b) * SHM_K + KSWZ(sr, kc)) = sr_[i].ks0;                       \
;     *(bf16x8*)((char*)K_lds + (b) * SHM_K + KSWZ(32 + sr, kc)) = sr_[i].ks1; } while (0)
; #define SWAIT() asm volatile("s_waitcnt vmcnt(4)" ::: "memory")
; #define RESC(a) do { if (__any((a) < 1.f)) { if (hi == 0) al_l[r32] = (a); asm volatile("s_waitcnt lgkmcnt(0)" ::: "memory"); \
;     _Pragma("unroll") for (int d = 0; d < 4; ++d) _Pragma("unroll") for (int r = 0; r < 16; ++r) o[d][r] *= al_l[crow(r, hi)]; } } while (0)
; __device__ __forceinline__ void partialSM(f32x16& p0, f32x16& p1, float& m_reg, float& mn, float& alpha) {
;     ...
;   float mnC = -mn * C;
; #pragma unroll
;   for (int r = 0; r < 16; ++r) p0[r] = fmaf(p0[r], C, mnC);
; #pragma unroll
;   for (int r = 0; r < 16; ++r) p1[r] = fmaf(p1[r], C, mnC);
; #pragma unroll
;   for (int r = 0; r < 16; ++r) p0[r] = __builtin_amdgcn_exp2f(p0[r]);
; template <int DLO, int DHI>
; __device__ __forceinline__ void attn_dense_body(const int g_wave, const bf16* __restrict__ Qb, const bf16* __restrict__ Kh, const bf16* __restrict__ Vh,
;                                                 bf16* __restrict__ Ob, int ldo, char* lds) {
;     ...
;     __syncthreads(); SWAIT(); SWRITE(0, SE);
;     RESC(alB); __syncthreads();
.LBB0_1047:
	v_cndmask_b32_e64 v230, v162, v170, s[8:9]
	v_mul_f32_e32 v231, 0xbe0293ee, v230
	v_fmamk_f32 v82, v82, 0x3e0293ee, v231
	v_fmamk_f32 v83, v83, 0x3e0293ee, v231
	v_fmamk_f32 v84, v84, 0x3e0293ee, v231
	v_fmamk_f32 v85, v85, 0x3e0293ee, v231
	v_fmamk_f32 v86, v86, 0x3e0293ee, v231
	v_fmamk_f32 v87, v87, 0x3e0293ee, v231
	v_fmamk_f32 v88, v88, 0x3e0293ee, v231
	v_fmamk_f32 v89, v89, 0x3e0293ee, v231
	v_fmamk_f32 v90, v90, 0x3e0293ee, v231
	v_fmamk_f32 v91, v91, 0x3e0293ee, v231
	v_fmamk_f32 v92, v92, 0x3e0293ee, v231
	v_fmamk_f32 v93, v93, 0x3e0293ee, v231
	v_fmamk_f32 v94, v94, 0x3e0293ee, v231
	v_fmamk_f32 v95, v95, 0x3e0293ee, v231
	v_fmamk_f32 v96, v96, 0x3e0293ee, v231
	v_fmamk_f32 v97, v97, 0x3e0293ee, v231
	v_exp_f32_e32 v162, v82
	v_exp_f32_e32 v177, v83
	v_exp_f32_e32 v163, v84
	v_exp_f32_e32 v176, v85
	v_exp_f32_e32 v164, v86
	v_exp_f32_e32 v175, v87
	v_exp_f32_e32 v165, v88
	v_exp_f32_e32 v174, v89
	v_exp_f32_e32 v166, v90
	v_exp_f32_e32 v173, v91
	v_exp_f32_e32 v167, v92
	v_exp_f32_e32 v172, v93
	v_exp_f32_e32 v168, v94
	v_exp_f32_e32 v171, v95
	v_exp_f32_e32 v169, v96
	v_exp_f32_e32 v170, v97
	v_fmamk_f32 v240, v66, 0x3e0293ee, v231
	v_fmamk_f32 v241, v67, 0x3e0293ee, v231
	v_fmamk_f32 v242, v68, 0x3e0293ee, v231
	v_fmamk_f32 v243, v69, 0x3e0293ee, v231
	v_fmamk_f32 v244, v70, 0x3e0293ee, v231
	v_fmamk_f32 v233, v71, 0x3e0293ee, v231
	v_fmamk_f32 v234, v72, 0x3e0293ee, v231
	v_fmamk_f32 v235, v73, 0x3e0293ee, v231
	v_fmamk_f32 v236, v74, 0x3e0293ee, v231
	v_fmamk_f32 v237, v75, 0x3e0293ee, v231
	v_fmamk_f32 v238, v76, 0x3e0293ee, v231
	v_fmamk_f32 v239, v77, 0x3e0293ee, v231
	v_fmamk_f32 v232, v78, 0x3e0293ee, v231
	v_fmamk_f32 v245, v79, 0x3e0293ee, v231
	v_fmamk_f32 v246, v80, 0x3e0293ee, v231
	v_fmac_f32_e32 v231, 0x3e0293ee, v81
	v_xor_b32_e32 v218, 0x10000, v218
	v_xor_b32_e32 v225, 0x10000, v225
	v_xor_b32_e32 v224, 0x10000, v224
	v_xor_b32_e32 v222, 0x10000, v222
	v_xor_b32_e32 v220, 0x10000, v220
	v_xor_b32_e32 v219, 0x10000, v219
	v_xor_b32_e32 v221, 0x10000, v221
	v_xor_b32_e32 v223, 0x10000, v223
	s_waitcnt lgkmcnt(0)
	s_barrier
; __device__ __forceinline__ void finishSM(f32x16& p0, f32x16& p1, float alpha, float& l_reg, bf16x8& pa0, bf16x8& pa1, bf16x8& pa2, bf16x8& pa3) {
; #pragma unroll
;   for (int r = 0; r < 16; ++r) p1[r] = __builtin_amdgcn_exp2f(p1[r]);
;   float ps = 0;
; #pragma unroll
;   for (int r = 0; r < 16; ++r) ps += p0[r];
; #pragma unroll
;   for (int r = 0; r < 16; ++r) ps += p1[r];
;   { auto rr = __builtin_amdgcn_permlane32_swap(__float_as_uint(ps), __float_as_uint(ps), false, false);
;     ps = __uint_as_float(rr[0]) + __uint_as_float(rr[1]); }
;   l_reg = l_reg * alpha + ps;
;   PK4(p0, 0, pa0); PK4(p0, 8, pa1); PK4(p1, 0, pa2); PK4(p1, 8, pa3);
; }
;   p0 = f32x16{}; p1 = f32x16{};
; #pragma unroll
;   for (int d0 = DLO; d0 < DHI; ++d0) { int cb = (d0 * 16 + hi * 8) * 2;
;     bf16x8 b0 = *reinterpret_cast<const bf16x8*>((const char*)Ks + KSWZ(r32, cb));
;     bf16x8 b1 = *reinterpret_cast<const bf16x8*>((const char*)Ks + KSWZ(32 + r32, cb));
;     p0 = __builtin_amdgcn_mfma_f32_32x32x16_bf16(b0, qr[d0], p0, 0, 0, 0);
;     p1 = __builtin_amdgcn_mfma_f32_32x32x16_bf16(b1, qr[d0], p1, 0, 0, 0); }
; }
	ds_read_b128 v[66:69], v218 offset:32768
	ds_read_b128 v[70:73], v218 offset:40960
	ds_read_b128 v[130:133], v225 offset:32768
	ds_read_b128 v[134:137], v225 offset:40960
	ds_read_b128 v[138:141], v224 offset:32768
	ds_read_b128 v[142:145], v224 offset:40960
	v_exp_f32_e32 v233, v233
	v_exp_f32_e32 v234, v234
	s_waitcnt lgkmcnt(4)
	v_mfma_f32_32x32x16_bf16 v[82:97], v[66:69], v[118:121], 0
	v_exp_f32_e32 v235, v235
	v_exp_f32_e32 v236, v236
	v_exp_f32_e32 v237, v237
	v_exp_f32_e32 v238, v238
	v_exp_f32_e32 v239, v239
	v_mfma_f32_32x32x16_bf16 v[66:81], v[70:73], v[118:121], 0
	s_waitcnt lgkmcnt(2)
	v_mfma_f32_32x32x16_bf16 v[82:97], v[130:133], v[110:113], v[82:97]
	v_mfma_f32_32x32x16_bf16 v[66:81], v[134:137], v[110:113], v[66:81]
	ds_read_b128 v[130:133], v222 offset:32768
	ds_read_b128 v[134:137], v222 offset:40960
	s_waitcnt lgkmcnt(2)
	v_mfma_f32_32x32x16_bf16 v[82:97], v[138:141], v[126:129], v[82:97]
	v_mfma_f32_32x32x16_bf16 v[66:81], v[142:145], v[126:129], v[66:81]
	ds_read_b128 v[138:141], v220 offset:32768
	ds_read_b128 v[142:145], v220 offset:40960
	s_waitcnt lgkmcnt(2)
	v_mfma_f32_32x32x16_bf16 v[82:97], v[130:133], v[122:125], v[82:97]
	v_mfma_f32_32x32x16_bf16 v[66:81], v[134:137], v[122:125], v[66:81]
	ds_read_b128 v[130:133], v219 offset:32768
	ds_read_b128 v[134:137], v219 offset:40960
	s_waitcnt lgkmcnt(2)
	v_mfma_f32_32x32x16_bf16 v[82:97], v[138:141], v[114:117], v[82:97]
	v_mfma_f32_32x32x16_bf16 v[66:81], v[142:145], v[114:117], v[66:81]
	ds_read_b128 v[138:141], v221 offset:32768
	ds_read_b128 v[142:145], v221 offset:40960
	s_waitcnt lgkmcnt(2)
	v_mfma_f32_32x32x16_bf16 v[82:97], v[130:133], v[106:109], v[82:97]
	v_mfma_f32_32x32x16_bf16 v[66:81], v[134:137], v[106:109], v[66:81]
	ds_read_b128 v[130:133], v223 offset:32768
	ds_read_b128 v[134:137], v223 offset:40960
	s_waitcnt lgkmcnt(2)
	v_mfma_f32_32x32x16_bf16 v[82:97], v[138:141], v[102:105], v[82:97]
	v_mfma_f32_32x32x16_bf16 v[66:81], v[142:145], v[102:105], v[66:81]
	s_waitcnt lgkmcnt(0)
	v_mfma_f32_32x32x16_bf16 v[82:97], v[130:133], v[98:101], v[82:97]
	v_exp_f32_e32 v186, v240
	v_exp_f32_e32 v240, v244
	v_exp_f32_e32 v244, v231
	v_add_f32_e32 v231, 0, v162
	v_add_f32_e32 v231, v177, v231
	v_add_f32_e32 v231, v163, v231
	v_add_f32_e32 v231, v176, v231
	v_add_f32_e32 v231, v164, v231
	v_add_f32_e32 v231, v175, v231
	v_add_f32_e32 v231, v165, v231
	v_add_f32_e32 v231, v174, v231
	v_add_f32_e32 v231, v166, v231
	v_add_f32_e32 v231, v173, v231
	v_add_f32_e32 v231, v167, v231
	v_add_f32_e32 v231, v172, v231
	v_add_f32_e32 v231, v168, v231
	v_exp_f32_e32 v187, v241
	v_add_f32_e32 v231, v171, v231
	v_exp_f32_e32 v188, v242
	v_add_f32_e32 v231, v169, v231
	v_exp_f32_e32 v189, v243
	v_add_f32_e32 v231, v170, v231
	v_add_f32_e32 v231, v186, v231
	v_add_f32_e32 v231, v187, v231
	v_add_f32_e32 v231, v188, v231
	v_add_f32_e32 v231, v189, v231
	v_add_f32_e32 v231, v240, v231
	v_add_f32_e32 v231, v233, v231
	v_add_f32_e32 v231, v234, v231
	v_add_f32_e32 v231, v235, v231
	v_exp_f32_e32 v241, v232
	v_add_f32_e32 v231, v236, v231
	v_exp_f32_e32 v242, v245
	v_add_f32_e32 v231, v237, v231
	v_mfma_f32_32x32x16_bf16 v[66:81], v[134:137], v[98:101], v[66:81]
	v_exp_f32_e32 v243, v246
	v_add_f32_e32 v231, v238, v231
	v_add_f32_e32 v231, v239, v231
	v_add_f32_e32 v231, v241, v231
	v_add_f32_e32 v231, v242, v231
	v_add_f32_e32 v231, v243, v231
	v_add_f32_e32 v231, v244, v231
	v_mov_b32_e32 v232, v231
	v_cvt_pk_bf16_f32 v162, v162, v177
	v_cvt_pk_bf16_f32 v163, v163, v176
	v_cvt_pk_bf16_f32 v164, v164, v175
	v_cvt_pk_bf16_f32 v165, v165, v174
	v_cvt_pk_bf16_f32 v166, v166, v173
	v_cvt_pk_bf16_f32 v167, v167, v172
	v_cvt_pk_bf16_f32 v168, v168, v171
	v_cvt_pk_bf16_f32 v169, v169, v170
	v_cvt_pk_bf16_f32 v170, v186, v187
	v_cvt_pk_bf16_f32 v171, v188, v189
	v_cvt_pk_bf16_f32 v172, v240, v233
	v_cvt_pk_bf16_f32 v173, v234, v235
	v_cvt_pk_bf16_f32 v174, v236, v237
	v_cvt_pk_bf16_f32 v175, v238, v239
	v_cvt_pk_bf16_f32 v176, v241, v242
	v_cvt_pk_bf16_f32 v177, v243, v244
	s_nop 1
	v_permlane32_swap_b32_e32 v231, v232
	v_permlane32_swap_b32_e32 v162, v164
	v_permlane32_swap_b32_e32 v163, v165
	v_permlane32_swap_b32_e32 v166, v168
	v_permlane32_swap_b32_e32 v167, v169
	v_permlane32_swap_b32_e32 v170, v172
	v_permlane32_swap_b32_e32 v171, v173
	v_permlane32_swap_b32_e32 v174, v176
	v_permlane32_swap_b32_e32 v175, v177
	s_waitcnt vmcnt(0)
	ds_write_b128 v216, v[146:149] offset:16384
	ds_write_b128 v217, v[150:153] offset:16384
	ds_write_b128 v214, v[154:157] offset:49152
	ds_write_b128 v215, v[158:161] offset:49152
	s_cmp_gt_u32 s34, 60
	s_cselect_b64 s[2:3], -1, 0
	s_and_b64 vcc, exec, s[2:3]
	s_cbranch_vccnz .LBB0_1049
	v_add_co_u32_e32 v130, vcc, 0x19040000, v196
	s_nop 1
	v_addc_co_u32_e32 v131, vcc, 0, v197, vcc
	v_add_co_u32_e32 v134, vcc, 0x19088000, v196
	s_nop 1
	v_addc_co_u32_e32 v135, vcc, 0, v197, vcc
	v_add_co_u32_e32 v138, vcc, 0x1f660000, v194
	global_load_dwordx4 v[130:133], v[130:131], off
	s_nop 0
	global_load_dwordx4 v[134:137], v[134:135], off
	v_addc_co_u32_e32 v139, vcc, 0, v195, vcc
	v_add_co_u32_e32 v142, vcc, 0x1f66c000, v194
	s_nop 1
	v_addc_co_u32_e32 v143, vcc, 0, v195, vcc
	global_load_dwordx4 v[138:141], v[138:139], off
	s_nop 0
	global_load_dwordx4 v[142:145], v[142:143], off
